# adds: up-projection epilogue vectors loaded from inside the K-loop (no vmcnt(0) drain), panel barrier with fire-and-forget arrival + early L1 invalidate, down-projection epilogue vector lines touched
# speedup vs baseline: 1.0175x; 1.0004x over previous
; #define LAS __attribute__((address_space(3)))
; __global__ void __launch_bounds__(512, 2) mk_fwd(Args args) {
;     extern __shared__ __attribute__((aligned(16))) unsigned char lds_raw[];
;     LAS unsigned char* lds = (LAS unsigned char*)lds_raw;
;     const int tid0 = threadIdx.x, G = gridDim.x, wg = blockIdx.x;
;     const int wv = __builtin_amdgcn_readfirstlane(tid0 >> 6);
;     ...
;     const int lo = args.ph_lo, hi = args.ph_hi;
;     ...
;     constexpr int lo = 0, hi = 2 + 3 * NSB + 1;
;     ...
;     unsigned char* ws = args.ws;
;     Ptrs P;
;     P.x = args.in[0]; P.c = args.in[1]; P.norm_ffn1 = args.in[2]; P.norm_mix = args.in[3]; P.norm_ffn2 = args.in[4]; P.w_ada = args.in[5]; P.b_ada = args.in[6];
;     P.w_ffn1_in = args.in[7]; P.w_ffn1_out = args.in[8]; P.w_ffn2_in = args.in[9]; P.w_ffn2_out = args.in[10]; P.conv_in = args.in[11]; P.conv_w = args.in[12]; P.conv_out = args.in[13];
;     P.pool_w = args.in[14]; P.pool_scale = args.in[15]; P.final_norm = args.in[16]; P.out = args.out; P.ws = ws;
;     if (tid0 < 18) *(LAS unsigned long long*)(lds + LDS_PTAB + 8 * tid0) = tid0 < 17 ? (unsigned long long)args.in[tid0 < 17 ? tid0 : 0] : (unsigned long long)args.out;
;     __syncthreads();
_Z6mk_fwd4Args:
	s_mov_b32 s101, 0
	s_load_dwordx2 s[92:93], s[0:1], 0x90
	v_readfirstlane_b32 s22, v0
	v_cmp_gt_u32_e32 vcc, 18, v0
	s_and_saveexec_b64 s[4:5], vcc
	s_cbranch_execz .LBB0_2
	s_add_u32 s3, s0, 0x88
	v_lshlrev_b32_e32 v2, 3, v0
	s_addc_u32 s6, s1, 0
	v_mov_b32_e32 v3, 0
	v_lshl_add_u64 v[4:5], s[0:1], 0, v[2:3]
	v_mov_b32_e32 v1, s6
	v_cmp_eq_u32_e32 vcc, 17, v0
	s_nop 1
	v_cndmask_b32_e32 v5, v5, v1, vcc
	v_mov_b32_e32 v1, s3
	v_cndmask_b32_e32 v4, v4, v1, vcc
	global_load_dwordx2 v[4:5], v[4:5], off
	v_add_u32_e32 v1, 0, v2
	v_add_u32_e32 v1, 0x23100, v1
	s_waitcnt vmcnt(0)
	ds_write_b64 v1, v[4:5]

; __device__ __forceinline__ unsigned xb_ld(unsigned* p)              { return __hip_atomic_load(p, __ATOMIC_RELAXED, __HIP_MEMORY_SCOPE_AGENT); }
; __device__ __forceinline__ unsigned xb_add(unsigned* p, unsigned v) { return __hip_atomic_fetch_add(p, v, __ATOMIC_RELAXED, __HIP_MEMORY_SCOPE_AGENT); }
; __device__ __forceinline__ void panel_barrier(unsigned* cnt, int tid) {
;     ...
;     if (tid == 0) {
;         __builtin_amdgcn_s_waitcnt(0);
;         const unsigned old = xb_add(cnt, 1u), target = (old & ~3u) + 4u;
;         unsigned sp = 0u;
;         while (xb_ld(cnt) < target) { __builtin_amdgcn_s_sleep(1); if (++sp > (1u << 26)) break; }
;         __builtin_amdgcn_fence(__ATOMIC_ACQUIRE, "agent");
;         asm volatile("s_waitcnt vmcnt(0)" ::: "memory");
;     }
;     __syncthreads();
.LBB0_304:
	s_or_b64 exec, exec, s[4:5]
	s_waitcnt vmcnt(0)

; #define LAS __attribute__((address_space(3)))
; #define GAS __attribute__((address_space(1)))
; #define PG8_STAGE(bufoff, gbase, unused) do { _Pragma("unroll") for (int _i = 0; _i < 2; ++_i) \
;         __builtin_amdgcn_global_load_lds((const unsigned*)((const char*)(gbase) + voff + _i * 8192), (LAS unsigned*)(lds + (bufoff) + ldsw + _i * 8192), 16, 0, 0); } while (0)
; #define PG8_WAIT_V(n) asm volatile("s_waitcnt vmcnt(" #n ")" ::: "memory")
; #define PG8_WAIT_L(n) asm volatile("s_waitcnt lgkmcnt(" #n ")" ::: "memory")
;     __device__ __forceinline__ void operator()(const f32x4 (&acc)[2][2][4][2], const Unit& u, int wr, int wc, int fr_, int fq_, LAS unsigned char* lds) const {
;     ...
;         const GAS float* bp = (const GAS float*)bias + (size_t)b * nbias + u.pn * BM + wc * 32 + 8 * fq;
;         const GAS float* cp = (const GAS float*)cw + u.pn * BM + wc * 32 + 8 * fq;
;         const LAS float* rfl = (const LAS float*)(lds + LDS_RED) + wr * 64 + fr;
;         float rf[2][4];
; #pragma unroll
;         for (int ai = 0; ai < 2; ++ai)
; #pragma unroll
;             for (int m = 0; m < 4; ++m) rf[ai][m] = rfl[ai * HALF + m * 16];
;         const unsigned lb8 = (unsigned)((fr * 64 + (wc & 1) * 32 + fq * 8) ^ ((fr >> 3) << 5));
;         const unsigned lb = (unsigned)((fr * 64 + fq * 16) ^ ((fr >> 3) << 5));
;         GAS char* o8 = (GAS char*)out + ((size_t)(2 * u.pm) * kt + u.pn) * HTB + (size_t)((8 * wr + (wc >> 1)) * 1024);
;         GAS char* ob = (GAS char*)out + ((size_t)(2 * u.pm) * kt + 2 * u.pn + (wc >> 1)) * HTB + (size_t)((8 * wr + (wc & 1)) * 1024);
;         const size_t hs = (size_t)kt * HTB;
; template <class Epi, class Sched, bool ALIGN_EPI, bool SP2, int MODE  >
; __device__ __forceinline__ void gemm_phase(LAS unsigned char* lds, const Gemm g, const Sched S, const Epi E, unsigned long long& probe_acc, int epi_id, int wv) {
;     ...
;             PG8_LDB(B0, 0, 0); PG8_LDB(B1, 0, 1); PG8_SCHED; PG8_LDA(At, 0, 0); PG8_STAGE(PG8_SA(1, 1), a1 + hA, voffA);
;             PG8_WAIT_V(8); PG8_WAIT_L(0); PG8_BAR; PG8_MMA(0, 0, At, B0); PG8_MMA(0, 1, At, B1); PG8_BAR; PG8_SCHED;
;             PG8_LDA(At, 0, 1); PG8_STAGE(PG8_SB(0, 0), b2, voffB); PG8_STAGE(PG8_SB(0, 1), b2 + hB, voffB); PG8_STAGE(PG8_SA(0, 0), a2, voffA);
;             PG8_WAIT_V(8); PG8_WAIT_L(0); PG8_BAR; PG8_MMA(1, 0, At, B0); PG8_MMA(1, 1, At, B1); PG8_BAR; PG8_SCHED;
.LBB0_326:
	v_add_u32_e32 v0, s39, v212
	ds_read_b128 v[132:135], v0
	ds_read_b128 v[136:139], v0 offset:1024
	ds_read_b128 v[140:143], v0 offset:2048
	ds_read_b128 v[144:147], v0 offset:3072
	v_add_u32_e32 v0, s65, v212
	ds_read_b128 v[148:151], v0
	ds_read_b128 v[152:155], v0 offset:1024
	ds_read_b128 v[156:159], v0 offset:2048
	ds_read_b128 v[160:163], v0 offset:3072
	s_add_u32 s30, s28, 0x8000
	s_addc_u32 s31, s29, 0
	s_cmp_eq_u32 s14, 12
	s_cselect_b32 s23, s27, s31
	s_cselect_b32 s22, s46, s30
	s_cselect_b32 s21, vcc_lo, s17
	s_cselect_b32 s20, vcc_hi, s16
	s_cmp_lg_u32 s14, 0
	s_cbranch_scc1 .Lhoist_i8in_skip
	s_lshr_b32 s98, s8, 4
	s_mul_i32 s98, s98, 0x2c00
	s_mov_b32 s99, 0
	s_lshl_b64 s[98:99], s[98:99], 2
	s_add_u32 s98, s6, s98
	s_addc_u32 s99, s7, s99
	s_lshl_b32 s100, s26, 10
	s_add_u32 s98, s98, s100
	s_addc_u32 s99, s99, 0
	s_add_u32 s98, s98, s9
	s_addc_u32 s99, s99, 0
	v_lshlrev_b32_e32 v218, 5, v195
	v_mov_b32_e32 v219, 0
	v_lshl_add_u64 v[216:217], s[98:99], 0, v[218:219]
	v_readlane_b32 s98, v255, 13
	v_readlane_b32 s99, v255, 14
	s_add_u32 s98, s98, s100
	s_addc_u32 s99, s99, 0
	v_lshl_add_u64 v[218:219], s[98:99], 0, v[218:219]
	global_load_dwordx4 v[220:223], v[216:217], off
	global_load_dwordx4 v[224:227], v[216:217], off offset:16
	global_load_dwordx4 v[228:231], v[216:217], off offset:512
	global_load_dwordx4 v[232:235], v[216:217], off offset:528
	global_load_dwordx4 v[236:239], v[218:219], off
	global_load_dwordx4 v[240:243], v[218:219], off offset:16
	global_load_dwordx4 v[244:247], v[218:219], off offset:512
	global_load_dwordx4 v[248:251], v[218:219], off offset:528
.Lhoist_i8in_skip:
	v_lshl_add_u64 v[184:185], s[28:29], 0, v[130:131]
	v_lshl_add_u64 v[204:205], v[184:185], 0, s[80:81]
	s_add_i32 m0, s85, 0xc000
	ds_read_b128 v[164:167], v213
	ds_read_b128 v[168:171], v213 offset:1024
	ds_read_b128 v[172:175], v213 offset:2048
	ds_read_b128 v[176:179], v213 offset:3072
	ds_read_b128 v[180:183], v213 offset:4096
	ds_read_b128 v[190:193], v213 offset:5120
	ds_read_b128 v[196:199], v213 offset:6144
	ds_read_b128 v[200:203], v213 offset:7168
	global_load_lds_dwordx4 v[204:205], off
	v_lshl_add_u64 v[184:185], v[184:185], 0, s[82:83]
	s_add_i32 m0, s85, 0xe000
	s_nop 0
	global_load_lds_dwordx4 v[184:185], off
	s_cmp_eq_u32 s14, 0
	s_cbranch_scc1 .Lhw_1a
	s_waitcnt vmcnt(8)
	s_branch .Lhw_1b
.Lhw_1a:
	s_waitcnt vmcnt(16)
.Lhw_1b:
	s_waitcnt lgkmcnt(0)
	s_barrier
	s_setprio 1
	s_waitcnt lgkmcnt(0)
	v_mfma_i32_16x16x64_i8 v[126:129], v[132:135], v[164:167], v[126:129]
	v_mfma_i32_16x16x64_i8 v[102:105], v[140:143], v[164:167], v[102:105]
	v_mfma_i32_16x16x64_i8 v[122:125], v[132:135], v[172:175], v[122:125]
	v_mfma_i32_16x16x64_i8 v[94:97], v[140:143], v[172:175], v[94:97]
	v_mfma_i32_16x16x64_i8 v[118:121], v[132:135], v[180:183], v[118:121]
	v_mfma_i32_16x16x64_i8 v[46:49], v[140:143], v[180:183], v[46:49]
	v_mfma_i32_16x16x64_i8 v[110:113], v[132:135], v[196:199], v[110:113]
	v_mfma_i32_16x16x64_i8 v[38:41], v[140:143], v[196:199], v[38:41]
	v_mfma_i32_16x16x64_i8 v[126:129], v[136:139], v[168:171], v[126:129]
	v_mfma_i32_16x16x64_i8 v[102:105], v[144:147], v[168:171], v[102:105]
	v_mfma_i32_16x16x64_i8 v[122:125], v[136:139], v[176:179], v[122:125]
	v_mfma_i32_16x16x64_i8 v[94:97], v[144:147], v[176:179], v[94:97]
	v_mfma_i32_16x16x64_i8 v[118:121], v[136:139], v[190:193], v[118:121]
	v_mfma_i32_16x16x64_i8 v[46:49], v[144:147], v[190:193], v[46:49]
	v_mfma_i32_16x16x64_i8 v[110:113], v[136:139], v[200:203], v[110:113]
	v_mfma_i32_16x16x64_i8 v[38:41], v[144:147], v[200:203], v[38:41]
	s_setprio 0
	s_setprio 1
	v_mfma_i32_16x16x64_i8 v[114:117], v[148:151], v[164:167], v[114:117]
	v_mfma_i32_16x16x64_i8 v[82:85], v[156:159], v[164:167], v[82:85]
	v_mfma_i32_16x16x64_i8 v[106:109], v[148:151], v[172:175], v[106:109]
	v_mfma_i32_16x16x64_i8 v[74:77], v[156:159], v[172:175], v[74:77]
	v_mfma_i32_16x16x64_i8 v[98:101], v[148:151], v[180:183], v[98:101]
	v_mfma_i32_16x16x64_i8 v[42:45], v[156:159], v[180:183], v[42:45]
	v_mfma_i32_16x16x64_i8 v[90:93], v[148:151], v[196:199], v[90:93]
	v_mfma_i32_16x16x64_i8 v[34:37], v[156:159], v[196:199], v[34:37]
	v_mfma_i32_16x16x64_i8 v[114:117], v[152:155], v[168:171], v[114:117]
	v_mfma_i32_16x16x64_i8 v[82:85], v[160:163], v[168:171], v[82:85]
	v_mfma_i32_16x16x64_i8 v[106:109], v[152:155], v[176:179], v[106:109]
	v_mfma_i32_16x16x64_i8 v[74:77], v[160:163], v[176:179], v[74:77]
	v_mfma_i32_16x16x64_i8 v[98:101], v[152:155], v[190:193], v[98:101]
	v_mfma_i32_16x16x64_i8 v[42:45], v[160:163], v[190:193], v[42:45]
	v_mfma_i32_16x16x64_i8 v[90:93], v[152:155], v[200:203], v[90:93]
	v_mfma_i32_16x16x64_i8 v[34:37], v[160:163], v[200:203], v[34:37]
	s_setprio 0
	s_barrier
	s_mov_b32 m0, s41
	v_lshl_add_u64 v[184:185], s[20:21], 0, v[130:131]
	ds_read_b128 v[164:167], v213 offset:16384
	ds_read_b128 v[168:171], v213 offset:17408
	ds_read_b128 v[172:175], v213 offset:18432
	ds_read_b128 v[176:179], v213 offset:19456
	ds_read_b128 v[180:183], v213 offset:20480
	ds_read_b128 v[190:193], v213 offset:21504
	ds_read_b128 v[196:199], v213 offset:22528
	ds_read_b128 v[200:203], v213 offset:23552
	global_load_lds_dwordx4 v[184:185], off
	v_lshl_add_u64 v[204:205], v[184:185], 0, s[70:71]
	s_mov_b32 m0, s64
	s_nop 0
	global_load_lds_dwordx4 v[204:205], off
	v_lshl_add_u64 v[204:205], v[184:185], 0, s[72:73]
	s_mov_b32 m0, s68
	s_nop 0
	global_load_lds_dwordx4 v[204:205], off
	v_lshl_add_u64 v[204:205], v[184:185], 0, s[74:75]
	s_mov_b32 m0, s84
	s_nop 0
	global_load_lds_dwordx4 v[204:205], off
	v_lshl_add_u64 v[204:205], s[22:23], 0, v[130:131]
	s_mov_b32 m0, s85
	v_lshl_add_u64 v[206:207], v[204:205], 0, s[70:71]
	global_load_lds_dwordx4 v[204:205], off
	s_mov_b32 m0, s86
	s_nop 0
	global_load_lds_dwordx4 v[206:207], off
	s_cmp_eq_u32 s14, 0
	s_cbranch_scc1 .Lhw_2a
	s_waitcnt vmcnt(8)
	s_branch .Lhw_2b

; #define PG8_STAGE(bufoff, gbase, unused) do { _Pragma("unroll") for (int _i = 0; _i < 2; ++_i) \
;         __builtin_amdgcn_global_load_lds((const unsigned*)((const char*)(gbase) + voff + _i * 8192), (LAS unsigned*)(lds + (bufoff) + ldsw + _i * 8192), 16, 0, 0); } while (0)
; #define PG8_LDA(dst, b, h) do { _Pragma("unroll") for (int m = 0; m < 4; ++m) _Pragma("unroll") for (int k = 0; k < 2; ++k) dst[m][k] = *(const LAS bf16x8*)(lds + PG8_SA(b, h) + aoff + m * 2048 + (FP8 ? k * 16 : k * 1024)); } while (0)
; #define PG8_LDB(dst, b, h) do { _Pragma("unroll") for (int n = 0; n < 2; ++n) _Pragma("unroll") for (int k = 0; k < 2; ++k) dst[n][k] = *(const LAS bf16x8*)(lds + PG8_SB(b, h) + boff + n * 2048 + (FP8 ? k * 16 : k * 1024)); } while (0)
; #define PG8_WAIT_V(n) asm volatile("s_waitcnt vmcnt(" #n ")" ::: "memory")
; #define PG8_WAIT_L(n) asm volatile("s_waitcnt lgkmcnt(" #n ")" ::: "memory")
; #define PG8_BAR __builtin_amdgcn_s_barrier()
; #define PG8_SCHED __builtin_amdgcn_sched_barrier(0)
; template <class Epi, class Sched, bool ALIGN_EPI, bool SP2, int MODE  >
; __device__ __forceinline__ void gemm_phase(LAS unsigned char* lds, const Gemm g, const Sched S, const Epi E, unsigned long long& probe_acc, int epi_id, int wv) {
;     ...
;             PG8_WAIT_V(8); PG8_WAIT_L(0); PG8_BAR; PG8_MMA(1, 0, At, B0); PG8_MMA(1, 1, At, B1); PG8_BAR; PG8_SCHED;
;             PG8_LDB(B0, 1, 0); PG8_LDB(B1, 1, 1); PG8_SCHED; PG8_LDA(At, 1, 0); PG8_STAGE(PG8_SA(0, 1), a2 + hA, voffA);
;             PG8_WAIT_V(8); PG8_WAIT_L(0); PG8_BAR; PG8_MMA(0, 0, At, B0); PG8_MMA(0, 1, At, B1); PG8_BAR; PG8_SCHED;
;             PG8_LDA(At, 1, 1); PG8_STAGE(PG8_SB(1, 0), b3, voffB); PG8_STAGE(PG8_SB(1, 1), b3 + hB, voffB); PG8_STAGE(PG8_SA(1, 0), a3, voffA);
.Lhw_2b:
	s_waitcnt lgkmcnt(0)
	s_barrier
	s_setprio 1
	s_waitcnt lgkmcnt(0)
	v_mfma_i32_16x16x64_i8 v[86:89], v[132:135], v[164:167], v[86:89]
	v_mfma_i32_16x16x64_i8 v[30:33], v[140:143], v[164:167], v[30:33]
	v_mfma_i32_16x16x64_i8 v[78:81], v[132:135], v[172:175], v[78:81]
	v_mfma_i32_16x16x64_i8 v[22:25], v[140:143], v[172:175], v[22:25]
	v_mfma_i32_16x16x64_i8 v[70:73], v[132:135], v[180:183], v[70:73]
	v_mfma_i32_16x16x64_i8 v[14:17], v[140:143], v[180:183], v[14:17]
	v_mfma_i32_16x16x64_i8 v[62:65], v[132:135], v[196:199], v[62:65]
	v_mfma_i32_16x16x64_i8 v[2:5], v[140:143], v[196:199], v[2:5]
	v_mfma_i32_16x16x64_i8 v[86:89], v[136:139], v[168:171], v[86:89]
	v_mfma_i32_16x16x64_i8 v[30:33], v[144:147], v[168:171], v[30:33]
	v_mfma_i32_16x16x64_i8 v[78:81], v[136:139], v[176:179], v[78:81]
	v_mfma_i32_16x16x64_i8 v[22:25], v[144:147], v[176:179], v[22:25]
	v_mfma_i32_16x16x64_i8 v[70:73], v[136:139], v[190:193], v[70:73]
	v_mfma_i32_16x16x64_i8 v[14:17], v[144:147], v[190:193], v[14:17]
	v_mfma_i32_16x16x64_i8 v[62:65], v[136:139], v[200:203], v[62:65]
	v_mfma_i32_16x16x64_i8 v[2:5], v[144:147], v[200:203], v[2:5]
	s_setprio 0
	s_setprio 1
	v_mfma_i32_16x16x64_i8 v[66:69], v[148:151], v[164:167], v[66:69]
	v_mfma_i32_16x16x64_i8 v[26:29], v[156:159], v[164:167], v[26:29]
	v_mfma_i32_16x16x64_i8 v[58:61], v[148:151], v[172:175], v[58:61]
	v_mfma_i32_16x16x64_i8 v[18:21], v[156:159], v[172:175], v[18:21]
	v_mfma_i32_16x16x64_i8 v[54:57], v[148:151], v[180:183], v[54:57]
	v_mfma_i32_16x16x64_i8 v[10:13], v[156:159], v[180:183], v[10:13]
	v_mfma_i32_16x16x64_i8 v[50:53], v[148:151], v[196:199], v[50:53]
	v_mfma_i32_16x16x64_i8 v[6:9], v[156:159], v[196:199], v[6:9]
	v_mfma_i32_16x16x64_i8 v[66:69], v[152:155], v[168:171], v[66:69]
	v_mfma_i32_16x16x64_i8 v[26:29], v[160:163], v[168:171], v[26:29]
	v_mfma_i32_16x16x64_i8 v[58:61], v[152:155], v[176:179], v[58:61]
	v_mfma_i32_16x16x64_i8 v[18:21], v[160:163], v[176:179], v[18:21]
	v_mfma_i32_16x16x64_i8 v[54:57], v[152:155], v[190:193], v[54:57]
	v_mfma_i32_16x16x64_i8 v[10:13], v[160:163], v[190:193], v[10:13]
	v_mfma_i32_16x16x64_i8 v[50:53], v[152:155], v[200:203], v[50:53]
	v_mfma_i32_16x16x64_i8 v[6:9], v[160:163], v[200:203], v[6:9]
	s_setprio 0
	s_barrier
	v_add_u32_e32 v0, s90, v212
	ds_read_b128 v[132:135], v0
	ds_read_b128 v[136:139], v0 offset:1024
	ds_read_b128 v[140:143], v0 offset:2048
	ds_read_b128 v[144:147], v0 offset:3072
	v_add_u32_e32 v0, s95, v212
	ds_read_b128 v[148:151], v0
	ds_read_b128 v[152:155], v0 offset:1024
	ds_read_b128 v[156:159], v0 offset:2048
	ds_read_b128 v[160:163], v0 offset:3072
	s_mov_b32 m0, s87
	v_lshl_add_u64 v[206:207], v[204:205], 0, s[72:73]
	ds_read_b128 v[164:167], v213 offset:32768
	ds_read_b128 v[168:171], v213 offset:33792
	ds_read_b128 v[172:175], v213 offset:34816
	ds_read_b128 v[176:179], v213 offset:35840
	ds_read_b128 v[180:183], v213 offset:36864
	ds_read_b128 v[190:193], v213 offset:37888
	ds_read_b128 v[196:199], v213 offset:38912
	ds_read_b128 v[200:203], v213 offset:39936
	global_load_lds_dwordx4 v[206:207], off
	v_lshl_add_u64 v[206:207], v[204:205], 0, s[74:75]
	s_mov_b32 m0, s88
	s_nop 0
	global_load_lds_dwordx4 v[206:207], off
	s_waitcnt vmcnt(8)
	s_waitcnt lgkmcnt(0)
	s_barrier
	s_setprio 1
	s_waitcnt lgkmcnt(0)
	v_mfma_i32_16x16x64_i8 v[126:129], v[132:135], v[164:167], v[126:129]
	v_mfma_i32_16x16x64_i8 v[102:105], v[140:143], v[164:167], v[102:105]
	v_mfma_i32_16x16x64_i8 v[122:125], v[132:135], v[172:175], v[122:125]
	v_mfma_i32_16x16x64_i8 v[94:97], v[140:143], v[172:175], v[94:97]
	v_mfma_i32_16x16x64_i8 v[118:121], v[132:135], v[180:183], v[118:121]
	v_mfma_i32_16x16x64_i8 v[46:49], v[140:143], v[180:183], v[46:49]
	v_mfma_i32_16x16x64_i8 v[110:113], v[132:135], v[196:199], v[110:113]
	v_mfma_i32_16x16x64_i8 v[38:41], v[140:143], v[196:199], v[38:41]
	v_mfma_i32_16x16x64_i8 v[126:129], v[136:139], v[168:171], v[126:129]
	v_mfma_i32_16x16x64_i8 v[102:105], v[144:147], v[168:171], v[102:105]
	v_mfma_i32_16x16x64_i8 v[122:125], v[136:139], v[176:179], v[122:125]
	v_mfma_i32_16x16x64_i8 v[94:97], v[144:147], v[176:179], v[94:97]
	v_mfma_i32_16x16x64_i8 v[118:121], v[136:139], v[190:193], v[118:121]
	v_mfma_i32_16x16x64_i8 v[46:49], v[144:147], v[190:193], v[46:49]
	v_mfma_i32_16x16x64_i8 v[110:113], v[136:139], v[200:203], v[110:113]
	v_mfma_i32_16x16x64_i8 v[38:41], v[144:147], v[200:203], v[38:41]
	s_setprio 0
	s_setprio 1
	v_mfma_i32_16x16x64_i8 v[114:117], v[148:151], v[164:167], v[114:117]
	v_mfma_i32_16x16x64_i8 v[82:85], v[156:159], v[164:167], v[82:85]
	v_mfma_i32_16x16x64_i8 v[106:109], v[148:151], v[172:175], v[106:109]
	v_mfma_i32_16x16x64_i8 v[74:77], v[156:159], v[172:175], v[74:77]
	v_mfma_i32_16x16x64_i8 v[98:101], v[148:151], v[180:183], v[98:101]
	v_mfma_i32_16x16x64_i8 v[42:45], v[156:159], v[180:183], v[42:45]
	v_mfma_i32_16x16x64_i8 v[90:93], v[148:151], v[196:199], v[90:93]
	v_mfma_i32_16x16x64_i8 v[34:37], v[156:159], v[196:199], v[34:37]
	v_mfma_i32_16x16x64_i8 v[114:117], v[152:155], v[168:171], v[114:117]
	v_mfma_i32_16x16x64_i8 v[82:85], v[160:163], v[168:171], v[82:85]
	v_mfma_i32_16x16x64_i8 v[106:109], v[152:155], v[176:179], v[106:109]
	v_mfma_i32_16x16x64_i8 v[74:77], v[160:163], v[176:179], v[74:77]
	v_mfma_i32_16x16x64_i8 v[98:101], v[152:155], v[190:193], v[98:101]
	v_mfma_i32_16x16x64_i8 v[42:45], v[160:163], v[190:193], v[42:45]
	v_mfma_i32_16x16x64_i8 v[90:93], v[152:155], v[200:203], v[90:93]
	v_mfma_i32_16x16x64_i8 v[34:37], v[160:163], v[200:203], v[34:37]
	s_setprio 0
	s_barrier
; #define GAS __attribute__((address_space(1)))
;     __device__ __forceinline__ void operator()(const f32x4 (&acc)[2][2][4][2], const Unit& u, int wr, int wc, int fr_, int fq_, LAS unsigned char* lds) const {
;         const int fr = opaque_v(fr_), fq = opaque_v(fq_);
;         const int b = u.pm >> 4;
;         f32x4 mx0 = {0.f, 0.f, 0.f, 0.f}, mx1 = mx0;
;         const GAS float* bp = (const GAS float*)bias + (size_t)b * nbias + u.pn * BM + wc * 32 + 8 * fq;
;         const GAS float* cp = (const GAS float*)cw + u.pn * BM + wc * 32 + 8 * fq;
; template <class Epi, class Sched, bool ALIGN_EPI, bool SP2, int MODE  >
; __device__ __forceinline__ void gemm_phase(LAS unsigned char* lds, const Gemm g, const Sched S, const Epi E, unsigned long long& probe_acc, int epi_id, int wv) {
;     ...
;             PG8_LDA(At, 1, 1); PG8_STAGE(PG8_SB(1, 0), b3, voffB); PG8_STAGE(PG8_SB(1, 1), b3 + hB, voffB); PG8_STAGE(PG8_SA(1, 0), a3, voffA);
;             PG8_WAIT_V(8); PG8_WAIT_L(0); PG8_BAR; PG8_MMA(1, 0, At, B0); PG8_MMA(1, 1, At, B1); PG8_BAR; PG8_SCHED;
;             } else {
;             PG8_LDB(B0, 0, 0); PG8_SCHED; PG8_LDA(At, 0, 0); PG8_STAGE(PG8_SA(1, 1), a1 + hA, voffA);
;             PG8_WAIT_L(8); PG8_BAR; PG8_WAIT_L(0); PG8_MMA(0, 0, At, B0); PG8_BAR; PG8_SCHED;
;             PG8_LDB(B1, 0, 1); PG8_STAGE(PG8_SB(0, 0), b2, voffB);
;             PG8_BAR; PG8_WAIT_L(0); PG8_MMA(0, 1, At, B1); PG8_BAR;
;             PG8_LDA(At, 0, 1); PG8_STAGE(PG8_SA(0, 0), a2, voffA);
;             PG8_BAR; PG8_WAIT_L(0); PG8_MMA(1, 0, At, B0); PG8_BAR; PG8_SCHED;
;             PG8_STAGE(PG8_SB(0, 1), b2 + hB, voffB);
;             PG8_WAIT_V(6); PG8_BAR; PG8_MMA(1, 1, At, B1); PG8_BAR;
;             PG8_LDB(B0, 1, 0); PG8_SCHED; PG8_LDA(At, 1, 0); PG8_STAGE(PG8_SA(0, 1), a2 + hA, voffA);
;             PG8_WAIT_L(8); PG8_BAR; PG8_WAIT_L(0); PG8_MMA(0, 0, At, B0); PG8_BAR; PG8_SCHED;
;             PG8_LDB(B1, 1, 1); PG8_STAGE(PG8_SB(1, 0), b3, voffB);
;             PG8_BAR; PG8_WAIT_L(0); PG8_MMA(0, 1, At, B1); PG8_BAR;
;             PG8_LDA(At, 1, 1); PG8_STAGE(PG8_SA(1, 0), a3, voffA);
;             PG8_BAR; PG8_WAIT_L(0); PG8_MMA(1, 0, At, B0); PG8_BAR; PG8_SCHED;
;             PG8_STAGE(PG8_SB(1, 1), b3 + hB, voffB);
;             PG8_WAIT_V(6); PG8_BAR; PG8_MMA(1, 1, At, B1); PG8_BAR;
;             }
;         }
;         if constexpr (ALIGN_EPI) { if (wr == 0) PG8_BAR; }
	s_mov_b32 m0, s91
	v_lshl_add_u64 v[206:207], v[184:185], 0, s[76:77]
	ds_read_b128 v[164:167], v213 offset:49152
	ds_read_b128 v[168:171], v213 offset:50176
	ds_read_b128 v[172:175], v213 offset:51200
	ds_read_b128 v[176:179], v213 offset:52224
	ds_read_b128 v[180:183], v213 offset:53248
	ds_read_b128 v[190:193], v213 offset:54272
	ds_read_b128 v[196:199], v213 offset:55296
	ds_read_b128 v[200:203], v213 offset:56320
	global_load_lds_dwordx4 v[206:207], off
	v_lshl_add_u64 v[206:207], v[184:185], 0, s[78:79]
	s_mov_b32 m0, s92
	s_nop 0
	global_load_lds_dwordx4 v[206:207], off
	v_lshl_add_u64 v[206:207], v[184:185], 0, s[80:81]
	s_mov_b32 m0, s2
	v_lshl_add_u64 v[184:185], v[184:185], 0, s[82:83]
	global_load_lds_dwordx4 v[206:207], off
	s_mov_b32 m0, s3
	s_nop 0
	global_load_lds_dwordx4 v[184:185], off
	v_lshl_add_u64 v[184:185], v[204:205], 0, s[76:77]
	s_mov_b32 m0, s93
	s_nop 0
	global_load_lds_dwordx4 v[184:185], off
	v_lshl_add_u64 v[184:185], v[204:205], 0, s[78:79]
	s_mov_b32 m0, s94
	s_nop 0
	global_load_lds_dwordx4 v[184:185], off
	s_waitcnt vmcnt(8)
	s_waitcnt lgkmcnt(0)
	s_barrier
	s_setprio 1
	s_waitcnt lgkmcnt(0)
	v_mfma_i32_16x16x64_i8 v[86:89], v[132:135], v[164:167], v[86:89]
	v_mfma_i32_16x16x64_i8 v[30:33], v[140:143], v[164:167], v[30:33]
	v_mfma_i32_16x16x64_i8 v[78:81], v[132:135], v[172:175], v[78:81]
	v_mfma_i32_16x16x64_i8 v[22:25], v[140:143], v[172:175], v[22:25]
	v_mfma_i32_16x16x64_i8 v[70:73], v[132:135], v[180:183], v[70:73]
	v_mfma_i32_16x16x64_i8 v[14:17], v[140:143], v[180:183], v[14:17]
	v_mfma_i32_16x16x64_i8 v[62:65], v[132:135], v[196:199], v[62:65]
	v_mfma_i32_16x16x64_i8 v[2:5], v[140:143], v[196:199], v[2:5]
	v_mfma_i32_16x16x64_i8 v[86:89], v[136:139], v[168:171], v[86:89]
	v_mfma_i32_16x16x64_i8 v[30:33], v[144:147], v[168:171], v[30:33]
	v_mfma_i32_16x16x64_i8 v[78:81], v[136:139], v[176:179], v[78:81]
	v_mfma_i32_16x16x64_i8 v[22:25], v[144:147], v[176:179], v[22:25]
	v_mfma_i32_16x16x64_i8 v[70:73], v[136:139], v[190:193], v[70:73]
	v_mfma_i32_16x16x64_i8 v[14:17], v[144:147], v[190:193], v[14:17]
	v_mfma_i32_16x16x64_i8 v[62:65], v[136:139], v[200:203], v[62:65]
	v_mfma_i32_16x16x64_i8 v[2:5], v[144:147], v[200:203], v[2:5]
	s_setprio 0
	s_setprio 1
	v_mfma_i32_16x16x64_i8 v[66:69], v[148:151], v[164:167], v[66:69]
	v_mfma_i32_16x16x64_i8 v[26:29], v[156:159], v[164:167], v[26:29]
	v_mfma_i32_16x16x64_i8 v[58:61], v[148:151], v[172:175], v[58:61]
	v_mfma_i32_16x16x64_i8 v[18:21], v[156:159], v[172:175], v[18:21]
	v_mfma_i32_16x16x64_i8 v[54:57], v[148:151], v[180:183], v[54:57]
	v_mfma_i32_16x16x64_i8 v[10:13], v[156:159], v[180:183], v[10:13]
	v_mfma_i32_16x16x64_i8 v[50:53], v[148:151], v[196:199], v[50:53]
	v_mfma_i32_16x16x64_i8 v[6:9], v[156:159], v[196:199], v[6:9]
	v_mfma_i32_16x16x64_i8 v[66:69], v[152:155], v[168:171], v[66:69]
	v_mfma_i32_16x16x64_i8 v[26:29], v[160:163], v[168:171], v[26:29]
	v_mfma_i32_16x16x64_i8 v[58:61], v[152:155], v[176:179], v[58:61]
	v_mfma_i32_16x16x64_i8 v[18:21], v[160:163], v[176:179], v[18:21]
	v_mfma_i32_16x16x64_i8 v[54:57], v[152:155], v[190:193], v[54:57]
	v_mfma_i32_16x16x64_i8 v[10:13], v[160:163], v[190:193], v[10:13]
	v_mfma_i32_16x16x64_i8 v[50:53], v[152:155], v[200:203], v[50:53]
	v_mfma_i32_16x16x64_i8 v[6:9], v[160:163], v[200:203], v[6:9]
	s_setprio 0
	s_barrier
	s_add_i32 s14, s14, 2
	s_add_u32 s16, s16, 0x8000
	s_addc_u32 s17, s17, 0
	s_cmp_gt_u32 s14, 13
	s_mov_b64 s[28:29], s[30:31]
	s_cbranch_scc0 .LBB0_326
	v_readlane_b32 s14, v255, 11
	v_readlane_b32 s15, v255, 12
	s_and_b64 vcc, exec, s[14:15]
	s_cbranch_vccz .LBB0_329
	s_barrier
.LBB0_329:
	s_lshr_b32 s14, s8, 4
	s_mul_i32 s46, s14, 0x2c00
	s_lshl_b32 s14, s26, 8
	s_ashr_i32 s15, s14, 31
	s_lshl_b64 s[14:15], s[14:15], 2
	v_readlane_b32 s16, v255, 13
	s_add_u32 s16, s16, s14
	v_readlane_b32 s17, v255, 14
	s_addc_u32 s17, s17, s15
	s_lshl_b64 s[20:21], s[46:47], 2
	v_mov_b32_e32 v214, v189
	s_add_u32 s20, s6, s20
	s_addc_u32 s21, s7, s21
	v_lshlrev_b32_e32 v0, 2, v214
	v_mov_b32_e32 v216, v195
	v_add_u32_e32 v132, s0, v0
	s_add_u32 s14, s20, s14
	ds_read2_b32 v[138:139], v132 offset1:16
	ds_read2_b32 v[136:137], v132 offset0:32 offset1:48
	ds_read2_b32 v[134:135], v132 offset0:128 offset1:144
	ds_read2_b32 v[132:133], v132 offset0:160 offset1:176
	v_lshlrev_b32_e32 v184, 3, v216
	s_addc_u32 s15, s21, s15
	v_ashrrev_i32_e32 v185, 31, v184
	s_add_u32 s14, s14, s9
	s_addc_u32 s15, s15, 0
	v_lshlrev_b64 v[140:141], 2, v[184:185]
	v_lshl_add_u64 v[182:183], s[14:15], 0, v[140:141]
	v_lshl_add_u64 v[180:181], s[16:17], 0, v[140:141]
	v_cvt_f32_i32_e32 v175, v129
	v_cvt_f32_i32_e32 v174, v128
	v_cvt_f32_i32_e32 v179, v127
	v_cvt_f32_i32_e32 v178, v126
	v_cvt_f32_i32_e32 v173, v117
	v_cvt_f32_i32_e32 v172, v116
	v_cvt_f32_i32_e32 v177, v115
	v_cvt_f32_i32_e32 v176, v114
	v_cvt_f32_i32_e32 v165, v125
	v_cvt_f32_i32_e32 v164, v124
	v_cvt_f32_i32_e32 v169, v123
	v_cvt_f32_i32_e32 v168, v122
	v_cvt_f32_i32_e32 v167, v109
	v_cvt_f32_i32_e32 v166, v108
	v_cvt_f32_i32_e32 v171, v107
	v_cvt_f32_i32_e32 v170, v106
	v_cvt_f32_i32_e32 v159, v121
	v_cvt_f32_i32_e32 v158, v120
	v_cvt_f32_i32_e32 v163, v119
	v_cvt_f32_i32_e32 v162, v118
	v_cvt_f32_i32_e32 v157, v101
	v_cvt_f32_i32_e32 v156, v100
	v_cvt_f32_i32_e32 v161, v99
	v_cvt_f32_i32_e32 v160, v98
	v_cvt_f32_i32_e32 v149, v113
	v_cvt_f32_i32_e32 v148, v112
	v_cvt_f32_i32_e32 v155, v111
	v_cvt_f32_i32_e32 v154, v110
	v_cvt_f32_i32_e32 v151, v93
	v_cvt_f32_i32_e32 v150, v92
	v_cvt_f32_i32_e32 v153, v91
	v_cvt_f32_i32_e32 v152, v90
	v_cvt_f32_i32_e32 v141, v89
	v_cvt_f32_i32_e32 v140, v88
	v_cvt_f32_i32_e32 v147, v87
	v_cvt_f32_i32_e32 v146, v86
	v_cvt_f32_i32_e32 v143, v69
	v_cvt_f32_i32_e32 v142, v68
	v_cvt_f32_i32_e32 v145, v67
	v_cvt_f32_i32_e32 v144, v66
	v_cvt_f32_i32_e32 v123, v81
	v_cvt_f32_i32_e32 v122, v80
	v_cvt_f32_i32_e32 v129, v79
	v_cvt_f32_i32_e32 v128, v78
	v_cvt_f32_i32_e32 v125, v61
	v_cvt_f32_i32_e32 v124, v60
	v_cvt_f32_i32_e32 v127, v59
	v_cvt_f32_i32_e32 v126, v58
	v_cvt_f32_i32_e32 v115, v73
	v_cvt_f32_i32_e32 v114, v72
	v_cvt_f32_i32_e32 v121, v71
	v_cvt_f32_i32_e32 v120, v70
	v_cvt_f32_i32_e32 v117, v57
	v_cvt_f32_i32_e32 v116, v56
	v_cvt_f32_i32_e32 v119, v55
	v_cvt_f32_i32_e32 v118, v54
	v_cvt_f32_i32_e32 v107, v65
	v_cvt_f32_i32_e32 v106, v64
	v_cvt_f32_i32_e32 v113, v63
	v_cvt_f32_i32_e32 v112, v62
	v_cvt_f32_i32_e32 v109, v53
	v_cvt_f32_i32_e32 v108, v52
	v_cvt_f32_i32_e32 v111, v51
	v_cvt_f32_i32_e32 v110, v50
	v_cvt_f32_i32_e32 v101, v105
	v_cvt_f32_i32_e32 v100, v104
	v_cvt_f32_i32_e32 v103, v103
	v_cvt_f32_i32_e32 v102, v102
	v_cvt_f32_i32_e32 v93, v85
	v_cvt_f32_i32_e32 v92, v84
	v_cvt_f32_i32_e32 v99, v83
	v_cvt_f32_i32_e32 v98, v82
	v_cvt_f32_i32_e32 v89, v97
	v_cvt_f32_i32_e32 v88, v96
	v_cvt_f32_i32_e32 v91, v95
	v_cvt_f32_i32_e32 v90, v94
	v_cvt_f32_i32_e32 v85, v77
	v_cvt_f32_i32_e32 v84, v76
	v_cvt_f32_i32_e32 v87, v75
	v_cvt_f32_i32_e32 v86, v74
	s_lshl_b32 s14, s8, 1
	v_lshlrev_b32_e32 v217, 6, v214
	v_and_b32_e32 v185, 0xffffffe0, v0
	v_lshlrev_b32_e32 v215, 4, v216
	s_mul_hi_u32 s30, s89, s14
	s_mul_i32 s31, s89, s14
	s_mov_b64 s[28:29], -1
	s_and_b64 vcc, exec, s[12:13]
	s_cbranch_vccz .LBB0_331
	v_mov_b64_e32 v[50:51], v[220:221]
	v_mov_b64_e32 v[52:53], v[222:223]
	v_mov_b64_e32 v[74:75], v[228:229]
	v_mov_b64_e32 v[76:77], v[230:231]
	v_mov_b64_e32 v[78:79], v[236:237]
	v_mov_b64_e32 v[80:81], v[238:239]
	v_mov_b64_e32 v[70:71], v[224:225]
	v_mov_b64_e32 v[72:73], v[226:227]
	v_mov_b64_e32 v[66:67], v[232:233]
	v_mov_b64_e32 v[68:69], v[234:235]
	v_mov_b64_e32 v[60:61], v[240:241]
	v_mov_b64_e32 v[62:63], v[242:243]
	v_mov_b64_e32 v[56:57], v[248:249]
	v_mov_b64_e32 v[58:59], v[250:251]
	v_mov_b64_e32 v[218:219], v[244:245]
	v_mov_b64_e32 v[220:221], v[246:247]
	s_lshl_b32 s14, s26, 1
	s_ashr_i32 s15, s14, 31
	s_add_u32 s14, s31, s14
	v_readlane_b32 s16, v255, 24
	s_addc_u32 s15, s30, s15
	v_readlane_b32 s17, v255, 25
	s_or_b64 s[14:15], s[14:15], s[16:17]
	s_lshl_b64 s[14:15], s[14:15], 14
	v_readlane_b32 s16, v255, 21
	s_add_u32 s28, s16, s14
	v_readlane_b32 s14, v255, 22
	s_waitcnt lgkmcnt(0)
	v_mov_b32_e32 v188, v139
	s_addc_u32 s29, s14, s15
	s_mov_b32 s14, 0xbfb8aa3b
	s_mov_b32 s20, 0x3fb8aa3b
	v_pk_mul_f32 v[64:65], v[138:139], v[174:175] op_sel_hi:[0,1]
	v_pk_mul_f32 v[228:229], v[188:189], v[164:165] op_sel_hi:[0,1]
	s_mov_b32 s16, 0xbf317218
	s_mov_b32 s22, 0x3f317218
	v_pk_mul_f32 v[54:55], v[138:139], v[178:179] op_sel_hi:[0,1]
	v_pk_mul_f32 v[104:105], v[138:139], v[172:173] op_sel_hi:[0,1]
	v_pk_mul_f32 v[204:205], v[136:137], v[162:163] op_sel_hi:[0,1]
	v_pk_mul_f32 v[206:207], v[136:137], v[158:159] op_sel_hi:[0,1]
	v_pk_mul_f32 v[226:227], v[188:189], v[168:169] op_sel_hi:[0,1]
	v_pk_mul_f32 v[232:233], v[188:189], v[166:167] op_sel_hi:[0,1]
	v_pk_mul_f32 v[94:95], v[138:139], v[176:177] op_sel_hi:[0,1]
	v_pk_mul_f32 v[230:231], v[188:189], v[170:171] op_sel_hi:[0,1]
	v_pk_mul_f32 v[224:225], v[136:137], v[156:157] op_sel_hi:[0,1]
	v_pk_mul_f32 v[222:223], v[136:137], v[160:161] op_sel_hi:[0,1]
	v_add_u32_e32 v0, v215, v217
	v_xor_b32_e32 v0, v0, v185
	v_lshl_add_u64 v[96:97], s[28:29], 0, v[0:1]
	v_pk_mul_f32 v[196:197], v[52:53], s[14:15] op_sel_hi:[1,0]
	v_pk_mul_f32 v[198:199], v[50:51], s[14:15] op_sel_hi:[1,0]
	v_pk_mul_f32 v[200:201], v[80:81], s[20:21] op_sel_hi:[1,0]
	v_pk_mul_f32 v[50:51], v[76:77], s[16:17] op_sel_hi:[1,0]
	v_pk_mul_f32 v[202:203], v[78:79], s[20:21] op_sel_hi:[1,0]
	v_pk_mul_f32 v[190:191], v[220:221], s[22:23] op_sel_hi:[1,0]
	v_pk_fma_f32 v[52:53], v[64:65], v[200:201], v[196:197] neg_lo:[1,0,0] neg_hi:[1,0,0]
	v_pk_fma_f32 v[76:77], v[228:229], v[200:201], v[196:197] neg_lo:[1,0,0] neg_hi:[1,0,0]
	v_pk_fma_f32 v[54:55], v[54:55], v[202:203], v[198:199] neg_lo:[1,0,0] neg_hi:[1,0,0]
	v_pk_fma_f32 v[64:65], v[104:105], v[190:191], v[50:51] neg_lo:[1,0,0] neg_hi:[1,0,0]
	v_pk_fma_f32 v[78:79], v[226:227], v[202:203], v[198:199] neg_lo:[1,0,0] neg_hi:[1,0,0]
	v_pk_fma_f32 v[104:105], v[206:207], v[200:201], v[196:197] neg_lo:[1,0,0] neg_hi:[1,0,0]
	v_pk_fma_f32 v[204:205], v[204:205], v[202:203], v[198:199] neg_lo:[1,0,0] neg_hi:[1,0,0]
	v_exp_f32_e32 v206, v52
	v_exp_f32_e32 v207, v53
	v_exp_f32_e32 v220, v76
	v_exp_f32_e32 v221, v77
	v_pk_mul_f32 v[192:193], v[218:219], s[22:23] op_sel_hi:[1,0]
	v_exp_f32_e32 v186, v54
	v_exp_f32_e32 v194, v55
	v_exp_f32_e32 v218, v78
	v_exp_f32_e32 v219, v79
	v_exp_f32_e32 v226, v204
	v_pk_mul_f32 v[82:83], v[74:75], s[16:17] op_sel_hi:[1,0]
	v_pk_fma_f32 v[80:81], v[232:233], v[190:191], v[50:51] neg_lo:[1,0,0] neg_hi:[1,0,0]
	v_add_f32_e32 v227, 1.0, v206
	v_add_f32_e32 v228, 1.0, v207
	v_add_f32_e32 v233, 1.0, v220
	v_add_f32_e32 v234, 1.0, v221
	v_pk_fma_f32 v[74:75], v[94:95], v[192:193], v[82:83] neg_lo:[1,0,0] neg_hi:[1,0,0]
	v_pk_fma_f32 v[94:95], v[230:231], v[192:193], v[82:83] neg_lo:[1,0,0] neg_hi:[1,0,0]
	v_add_f32_e32 v186, 1.0, v186
	v_add_f32_e32 v194, 1.0, v194
	v_add_f32_e32 v231, 1.0, v218
	v_add_f32_e32 v232, 1.0, v219
	v_add_f32_e32 v235, 1.0, v226
	v_rcp_f32_e32 v218, v227
	v_rcp_f32_e32 v219, v228
	v_rcp_f32_e32 v226, v233
	v_rcp_f32_e32 v227, v234
	v_rcp_f32_e32 v206, v186
	v_rcp_f32_e32 v207, v194
	v_rcp_f32_e32 v220, v231
	v_rcp_f32_e32 v221, v232
	v_pk_mul_f32 v[52:53], v[52:53], v[218:219]
	v_pk_mul_f32 v[76:77], v[76:77], v[226:227]
	v_pk_mul_f32 v[54:55], v[54:55], v[206:207]
	v_pk_mul_f32 v[78:79], v[78:79], v[220:221]
	v_pk_mul_f32 v[52:53], v[64:65], v[52:53]
	v_pk_mul_f32 v[64:65], v[80:81], v[76:77]
	v_pk_mul_f32 v[54:55], v[74:75], v[54:55]
	v_pk_mul_f32 v[74:75], v[94:95], v[78:79]
	v_cvt_pk_bf16_f32 v80, v54, v55
	v_cvt_pk_bf16_f32 v81, v52, v53
	v_max_f32_e64 v52, |v52|, |v53|
	v_max_f32_e64 v53, |v64|, |v65|
	v_exp_f32_e32 v230, v104
	v_max3_f32 v226, |v74|, |v75|, v53
	v_exp_f32_e32 v53, v105
	v_exp_f32_e32 v229, v205
	v_max3_f32 v221, |v54|, |v55|, v52
	v_add_f32_e32 v52, 1.0, v230
	v_add_f32_e32 v53, 1.0, v53
	v_add_f32_e32 v54, 1.0, v229
	v_rcp_f32_e32 v52, v52
	v_rcp_f32_e32 v53, v53
	v_rcp_f32_e32 v228, v235
	v_rcp_f32_e32 v229, v54
	v_pk_fma_f32 v[54:55], v[224:225], v[190:191], v[50:51] neg_lo:[1,0,0] neg_hi:[1,0,0]
	v_pk_mul_f32 v[52:53], v[104:105], v[52:53]
	v_cvt_pk_bf16_f32 v78, v74, v75
	v_cvt_pk_bf16_f32 v79, v64, v65
	v_pk_fma_f32 v[64:65], v[222:223], v[192:193], v[82:83] neg_lo:[1,0,0] neg_hi:[1,0,0]
	v_pk_mul_f32 v[74:75], v[204:205], v[228:229]
	v_pk_mul_f32 v[52:53], v[54:55], v[52:53]
	v_pk_mul_f32 v[54:55], v[64:65], v[74:75]
	v_mov_b32_e32 v194, v137
	v_cvt_pk_bf16_f32 v76, v54, v55
	v_cvt_pk_bf16_f32 v77, v52, v53
	v_max_f32_e64 v52, |v52|, |v53|
	v_max3_f32 v227, |v54|, |v55|, v52
	v_pk_mul_f32 v[54:55], v[194:195], v[148:149] op_sel_hi:[0,1]
	v_pk_mul_f32 v[52:53], v[194:195], v[154:155] op_sel_hi:[0,1]
	v_pk_fma_f32 v[54:55], v[54:55], v[200:201], v[196:197] neg_lo:[1,0,0] neg_hi:[1,0,0]
	v_pk_fma_f32 v[52:53], v[52:53], v[202:203], v[198:199] neg_lo:[1,0,0] neg_hi:[1,0,0]
	v_exp_f32_e32 v104, v54
	v_exp_f32_e32 v105, v55
	v_exp_f32_e32 v94, v52
	v_exp_f32_e32 v95, v53
	v_add_f32_e32 v104, 1.0, v104
	v_add_f32_e32 v105, 1.0, v105
	v_add_f32_e32 v94, 1.0, v94
	v_add_f32_e32 v95, 1.0, v95
	v_rcp_f32_e32 v104, v104
	v_rcp_f32_e32 v105, v105
	v_rcp_f32_e32 v94, v94
	v_rcp_f32_e32 v95, v95
	v_pk_mul_f32 v[74:75], v[194:195], v[150:151] op_sel_hi:[0,1]
	v_pk_mul_f32 v[64:65], v[194:195], v[152:153] op_sel_hi:[0,1]
	v_pk_fma_f32 v[74:75], v[74:75], v[190:191], v[50:51] neg_lo:[1,0,0] neg_hi:[1,0,0]
	v_pk_mul_f32 v[54:55], v[54:55], v[104:105]
	v_pk_fma_f32 v[64:65], v[64:65], v[192:193], v[82:83] neg_lo:[1,0,0] neg_hi:[1,0,0]
	v_pk_mul_f32 v[52:53], v[52:53], v[94:95]
	v_pk_mul_f32 v[54:55], v[74:75], v[54:55]
	v_pk_mul_f32 v[52:53], v[64:65], v[52:53]
	v_pk_mul_f32 v[104:105], v[134:135], v[142:143] op_sel_hi:[0,1]
	v_cvt_pk_bf16_f32 v74, v52, v53
	v_cvt_pk_bf16_f32 v75, v54, v55
	v_max_f32_e64 v54, |v54|, |v55|
	v_max3_f32 v228, |v52|, |v53|, v54
	v_pk_mul_f32 v[52:53], v[134:135], v[146:147] op_sel_hi:[0,1]
	v_pk_fma_f32 v[52:53], v[52:53], v[202:203], v[198:199] neg_lo:[1,0,0] neg_hi:[1,0,0]
	v_pk_mul_f32 v[54:55], v[134:135], v[140:141] op_sel_hi:[0,1]
	v_exp_f32_e32 v186, v52
	v_pk_fma_f32 v[54:55], v[54:55], v[200:201], v[196:197] neg_lo:[1,0,0] neg_hi:[1,0,0]
	v_exp_f32_e32 v205, v53
	v_exp_f32_e32 v206, v54
	v_add_f32_e32 v186, 1.0, v186
	v_rcp_f32_e32 v204, v186
	v_exp_f32_e32 v186, v55
	v_add_f32_e32 v206, 1.0, v206
	v_add_f32_e32 v205, 1.0, v205
	v_rcp_f32_e32 v206, v206
	v_add_f32_e32 v186, 1.0, v186
	v_rcp_f32_e32 v207, v186
	v_rcp_f32_e32 v205, v205
	v_pk_mul_f32 v[64:65], v[134:135], v[144:145] op_sel_hi:[0,1]
	v_pk_fma_f32 v[104:105], v[104:105], v[190:191], v[50:51] neg_lo:[1,0,0] neg_hi:[1,0,0]
	v_pk_mul_f32 v[54:55], v[54:55], v[206:207]
	v_pk_fma_f32 v[64:65], v[64:65], v[192:193], v[82:83] neg_lo:[1,0,0] neg_hi:[1,0,0]
	v_pk_mul_f32 v[52:53], v[52:53], v[204:205]
	v_pk_mul_f32 v[54:55], v[104:105], v[54:55]
	v_pk_mul_f32 v[52:53], v[64:65], v[52:53]
	v_mov_b32_e32 v186, v135
	v_cvt_pk_bf16_f32 v64, v52, v53
	v_cvt_pk_bf16_f32 v65, v54, v55
	v_max_f32_e64 v54, |v54|, |v55|
	v_max3_f32 v220, |v52|, |v53|, v54
	v_pk_mul_f32 v[54:55], v[186:187], v[122:123] op_sel_hi:[0,1]
	v_pk_mul_f32 v[52:53], v[186:187], v[128:129] op_sel_hi:[0,1]
	v_pk_fma_f32 v[54:55], v[54:55], v[200:201], v[196:197] neg_lo:[1,0,0] neg_hi:[1,0,0]
	v_pk_fma_f32 v[52:53], v[52:53], v[202:203], v[198:199] neg_lo:[1,0,0] neg_hi:[1,0,0]
	v_exp_f32_e32 v218, v54
	v_exp_f32_e32 v219, v55
	v_exp_f32_e32 v206, v52
	v_exp_f32_e32 v207, v53
	v_add_f32_e32 v218, 1.0, v218
	v_add_f32_e32 v219, 1.0, v219
	v_add_f32_e32 v206, 1.0, v206
	v_add_f32_e32 v207, 1.0, v207
	v_rcp_f32_e32 v218, v218
	v_rcp_f32_e32 v219, v219
	v_rcp_f32_e32 v206, v206
	v_rcp_f32_e32 v207, v207
	v_pk_mul_f32 v[204:205], v[186:187], v[124:125] op_sel_hi:[0,1]
	v_pk_mul_f32 v[104:105], v[186:187], v[126:127] op_sel_hi:[0,1]
	v_pk_fma_f32 v[204:205], v[204:205], v[190:191], v[50:51] neg_lo:[1,0,0] neg_hi:[1,0,0]
	v_pk_mul_f32 v[54:55], v[54:55], v[218:219]
	v_pk_fma_f32 v[104:105], v[104:105], v[192:193], v[82:83] neg_lo:[1,0,0] neg_hi:[1,0,0]
	v_pk_mul_f32 v[52:53], v[52:53], v[206:207]
	v_pk_mul_f32 v[204:205], v[204:205], v[54:55]
	v_pk_mul_f32 v[52:53], v[104:105], v[52:53]
	v_max_f32_e64 v104, |v204|, |v205|
	v_cvt_pk_bf16_f32 v54, v52, v53
	v_max3_f32 v219, |v52|, |v53|, v104
	v_pk_mul_f32 v[52:53], v[132:133], v[120:121] op_sel_hi:[0,1]
	v_pk_fma_f32 v[52:53], v[52:53], v[202:203], v[198:199] neg_lo:[1,0,0] neg_hi:[1,0,0]
	v_pk_mul_f32 v[104:105], v[132:133], v[114:115] op_sel_hi:[0,1]
	v_exp_f32_e32 v218, v52
	v_pk_fma_f32 v[104:105], v[104:105], v[200:201], v[196:197] neg_lo:[1,0,0] neg_hi:[1,0,0]
	v_exp_f32_e32 v223, v53
	v_exp_f32_e32 v224, v104
	v_add_f32_e32 v218, 1.0, v218
	v_rcp_f32_e32 v222, v218
	v_exp_f32_e32 v218, v105
	v_add_f32_e32 v224, 1.0, v224
	v_add_f32_e32 v223, 1.0, v223
	v_rcp_f32_e32 v224, v224
	v_add_f32_e32 v218, 1.0, v218
	v_rcp_f32_e32 v225, v218
	v_rcp_f32_e32 v223, v223
	v_pk_mul_f32 v[206:207], v[132:133], v[116:117] op_sel_hi:[0,1]
	v_cvt_pk_bf16_f32 v55, v204, v205
	v_pk_mul_f32 v[204:205], v[132:133], v[118:119] op_sel_hi:[0,1]
	v_pk_fma_f32 v[206:207], v[206:207], v[190:191], v[50:51] neg_lo:[1,0,0] neg_hi:[1,0,0]
	v_pk_mul_f32 v[104:105], v[104:105], v[224:225]
	v_pk_fma_f32 v[204:205], v[204:205], v[192:193], v[82:83] neg_lo:[1,0,0] neg_hi:[1,0,0]
	v_pk_mul_f32 v[52:53], v[52:53], v[222:223]
	v_pk_mul_f32 v[104:105], v[206:207], v[104:105]
	v_pk_mul_f32 v[204:205], v[204:205], v[52:53]
	v_pk_mul_f32 v[72:73], v[72:73], s[14:15] op_sel_hi:[1,0]
	v_cvt_pk_bf16_f32 v52, v204, v205
	v_cvt_pk_bf16_f32 v53, v104, v105
	v_max_f32_e64 v104, |v104|, |v105|
	v_max3_f32 v218, |v204|, |v205|, v104
	v_mov_b32_e32 v104, v133
	v_pk_mul_f32 v[204:205], v[104:105], v[112:113] op_sel_hi:[0,1]
	v_pk_fma_f32 v[198:199], v[204:205], v[202:203], v[198:199] neg_lo:[1,0,0] neg_hi:[1,0,0]
	v_pk_mul_f32 v[206:207], v[104:105], v[106:107] op_sel_hi:[0,1]
	v_exp_f32_e32 v105, v198
	v_pk_fma_f32 v[196:197], v[206:207], v[200:201], v[196:197] neg_lo:[1,0,0] neg_hi:[1,0,0]
	v_exp_f32_e32 v201, v199
	v_exp_f32_e32 v206, v196
	v_pk_mul_f32 v[202:203], v[104:105], v[110:111] op_sel_hi:[0,1]
	v_pk_mul_f32 v[204:205], v[104:105], v[108:109] op_sel_hi:[0,1]
	v_add_f32_e32 v105, 1.0, v105
	v_rcp_f32_e32 v200, v105
	v_exp_f32_e32 v105, v197
	v_add_f32_e32 v206, 1.0, v206
	v_add_f32_e32 v201, 1.0, v201
	v_rcp_f32_e32 v206, v206
	v_add_f32_e32 v105, 1.0, v105
	v_rcp_f32_e32 v207, v105
	v_rcp_f32_e32 v201, v201
	v_pk_fma_f32 v[50:51], v[204:205], v[190:191], v[50:51] neg_lo:[1,0,0] neg_hi:[1,0,0]
	v_pk_fma_f32 v[82:83], v[202:203], v[192:193], v[82:83] neg_lo:[1,0,0] neg_hi:[1,0,0]
	v_pk_mul_f32 v[190:191], v[196:197], v[206:207]
	v_pk_mul_f32 v[192:193], v[198:199], v[200:201]
	v_pk_mul_f32 v[190:191], v[50:51], v[190:191]
	v_pk_mul_f32 v[82:83], v[82:83], v[192:193]
	v_max_f32_e64 v105, |v190|, |v191|
	v_cvt_pk_bf16_f32 v50, v82, v83
	v_cvt_pk_bf16_f32 v51, v190, v191
	v_pk_mul_f32 v[190:191], v[70:71], s[14:15] op_sel_hi:[1,0]
	v_pk_mul_f32 v[192:193], v[60:61], s[20:21] op_sel_hi:[1,0]
	v_pk_mul_f32 v[60:61], v[56:57], s[22:23] op_sel_hi:[1,0]
	v_pk_mul_f32 v[56:57], v[138:139], v[102:103] op_sel_hi:[0,1]
	v_pk_fma_f32 v[56:57], v[56:57], v[192:193], v[190:191] neg_lo:[1,0,0] neg_hi:[1,0,0]
	v_max3_f32 v196, |v82|, |v83|, v105
	v_exp_f32_e32 v105, v56
	v_pk_mul_f32 v[70:71], v[66:67], s[16:17] op_sel_hi:[1,0]
	v_pk_mul_f32 v[62:63], v[62:63], s[20:21] op_sel_hi:[1,0]
	v_pk_mul_f32 v[66:67], v[138:139], v[100:101] op_sel_hi:[0,1]
	v_pk_fma_f32 v[66:67], v[66:67], v[62:63], v[72:73] neg_lo:[1,0,0] neg_hi:[1,0,0]
	v_add_f32_e32 v105, 1.0, v105
	v_exp_f32_e32 v201, v66
	v_rcp_f32_e32 v200, v105
	v_exp_f32_e32 v105, v67
	v_exp_f32_e32 v197, v57
	v_add_f32_e32 v201, 1.0, v201
	v_rcp_f32_e32 v202, v201
	v_add_f32_e32 v105, 1.0, v105
	v_add_f32_e32 v197, 1.0, v197
	v_rcp_f32_e32 v203, v105
	v_rcp_f32_e32 v201, v197
	v_pk_mul_f32 v[68:69], v[68:69], s[16:17] op_sel_hi:[1,0]
	v_pk_mul_f32 v[58:59], v[58:59], s[22:23] op_sel_hi:[1,0]
	v_pk_mul_f32 v[198:199], v[138:139], v[92:93] op_sel_hi:[0,1]
	v_pk_mul_f32 v[82:83], v[138:139], v[98:99] op_sel_hi:[0,1]
	v_pk_fma_f32 v[198:199], v[198:199], v[58:59], v[68:69] neg_lo:[1,0,0] neg_hi:[1,0,0]
	v_pk_mul_f32 v[66:67], v[66:67], v[202:203]
	v_pk_fma_f32 v[82:83], v[82:83], v[60:61], v[70:71] neg_lo:[1,0,0] neg_hi:[1,0,0]
	v_pk_mul_f32 v[56:57], v[56:57], v[200:201]
	v_pk_mul_f32 v[66:67], v[198:199], v[66:67]
	v_pk_mul_f32 v[56:57], v[82:83], v[56:57]
	s_movk_i32 s14, 0x1000
	v_cvt_pk_bf16_f32 v82, v56, v57
	v_cvt_pk_bf16_f32 v83, v66, v67
	v_max_f32_e64 v66, |v66|, |v67|
	v_max3_f32 v56, |v56|, |v57|, v66
	v_max3_f32 v105, v221, 0, v56
	v_pk_mul_f32 v[56:57], v[188:189], v[90:91] op_sel_hi:[0,1]
	v_pk_fma_f32 v[56:57], v[56:57], v[192:193], v[190:191] neg_lo:[1,0,0] neg_hi:[1,0,0]
	v_pk_mul_f32 v[66:67], v[188:189], v[88:89] op_sel_hi:[0,1]
	v_exp_f32_e32 v197, v56
	global_store_dwordx4 v0, v[80:83], s[28:29]
	v_pk_fma_f32 v[66:67], v[66:67], v[62:63], v[72:73] neg_lo:[1,0,0] neg_hi:[1,0,0]
	v_lshl_add_u64 v[94:95], v[96:97], 0, s[18:19]
	v_pk_mul_f32 v[80:81], v[188:189], v[86:87] op_sel_hi:[0,1]
	v_pk_mul_f32 v[82:83], v[188:189], v[84:85] op_sel_hi:[0,1]
	v_add_f32_e32 v188, 1.0, v197
	v_exp_f32_e32 v199, v66
	v_rcp_f32_e32 v198, v188
	v_exp_f32_e32 v188, v67
	v_exp_f32_e32 v197, v57
	v_add_f32_e32 v199, 1.0, v199
	v_rcp_f32_e32 v200, v199
	v_add_f32_e32 v188, 1.0, v188
	v_add_f32_e32 v197, 1.0, v197
	v_rcp_f32_e32 v201, v188
	v_rcp_f32_e32 v199, v197
	v_pk_fma_f32 v[82:83], v[82:83], v[58:59], v[68:69] neg_lo:[1,0,0] neg_hi:[1,0,0]
	v_pk_fma_f32 v[80:81], v[80:81], v[60:61], v[70:71] neg_lo:[1,0,0] neg_hi:[1,0,0]
	v_pk_mul_f32 v[66:67], v[66:67], v[200:201]
	v_pk_mul_f32 v[56:57], v[56:57], v[198:199]
	v_pk_mul_f32 v[66:67], v[82:83], v[66:67]
	v_pk_mul_f32 v[56:57], v[80:81], v[56:57]
	s_nop 0
	v_cvt_pk_bf16_f32 v80, v56, v57
	v_cvt_pk_bf16_f32 v81, v66, v67
	v_max_f32_e64 v66, |v66|, |v67|
	v_max3_f32 v82, |v56|, |v57|, v66
	v_cvt_f32_i32_e32 v67, v47
	v_cvt_f32_i32_e32 v66, v46
	v_cvt_f32_i32_e32 v57, v49
	v_cvt_f32_i32_e32 v56, v48
	global_store_dwordx4 v0, v[78:81], s[28:29] offset:2048
	v_pk_mul_f32 v[66:67], v[136:137], v[66:67] op_sel_hi:[0,1]
	v_pk_fma_f32 v[66:67], v[66:67], v[192:193], v[190:191] neg_lo:[1,0,0] neg_hi:[1,0,0]
	v_pk_mul_f32 v[56:57], v[136:137], v[56:57] op_sel_hi:[0,1]
	v_exp_f32_e32 v0, v66
	v_pk_fma_f32 v[56:57], v[56:57], v[62:63], v[72:73] neg_lo:[1,0,0] neg_hi:[1,0,0]
	v_exp_f32_e32 v83, v67
	v_exp_f32_e32 v188, v56
	v_add_f32_e32 v0, 1.0, v0
	v_rcp_f32_e32 v198, v0
	v_exp_f32_e32 v0, v57
	v_cvt_f32_i32_e32 v79, v45
	v_cvt_f32_i32_e32 v78, v44
	v_add_f32_e32 v188, 1.0, v188
	v_add_f32_e32 v0, 1.0, v0
	v_cvt_f32_i32_e32 v81, v43
	v_cvt_f32_i32_e32 v80, v42
	v_add_f32_e32 v83, 1.0, v83
	v_rcp_f32_e32 v200, v188
	v_rcp_f32_e32 v201, v0
	v_rcp_f32_e32 v199, v83
	v_pk_mul_f32 v[78:79], v[136:137], v[78:79] op_sel_hi:[0,1]
	v_pk_mul_f32 v[80:81], v[136:137], v[80:81] op_sel_hi:[0,1]
	v_pk_fma_f32 v[78:79], v[78:79], v[58:59], v[68:69] neg_lo:[1,0,0] neg_hi:[1,0,0]
	v_pk_mul_f32 v[56:57], v[56:57], v[200:201]
	v_pk_fma_f32 v[80:81], v[80:81], v[60:61], v[70:71] neg_lo:[1,0,0] neg_hi:[1,0,0]
	v_pk_mul_f32 v[66:67], v[66:67], v[198:199]
	v_pk_mul_f32 v[56:57], v[78:79], v[56:57]
	v_pk_mul_f32 v[66:67], v[80:81], v[66:67]
	v_max_f32_e64 v0, |v56|, |v57|
	v_cvt_pk_bf16_f32 v78, v66, v67
	v_max3_f32 v0, |v66|, |v67|, v0
	v_cvt_f32_i32_e32 v67, v39
	v_cvt_f32_i32_e32 v66, v38
	v_cvt_pk_bf16_f32 v79, v56, v57
	v_cvt_f32_i32_e32 v57, v41
	v_cvt_f32_i32_e32 v56, v40
	v_pk_mul_f32 v[66:67], v[194:195], v[66:67] op_sel_hi:[0,1]
	v_pk_fma_f32 v[66:67], v[66:67], v[192:193], v[190:191] neg_lo:[1,0,0] neg_hi:[1,0,0]
	v_add_co_u32_e32 v80, vcc, s14, v96
	v_exp_f32_e32 v83, v66
	v_pk_mul_f32 v[56:57], v[194:195], v[56:57] op_sel_hi:[0,1]
	v_pk_fma_f32 v[56:57], v[56:57], v[62:63], v[72:73] neg_lo:[1,0,0] neg_hi:[1,0,0]
	v_addc_co_u32_e32 v81, vcc, 0, v97, vcc
	v_add_f32_e32 v83, 1.0, v83
	v_exp_f32_e32 v188, v56
	v_rcp_f32_e32 v96, v83
	v_exp_f32_e32 v83, v57
	v_exp_f32_e32 v97, v67
	global_store_dwordx4 v[80:81], v[76:79], off
	v_add_f32_e32 v188, 1.0, v188
	v_add_f32_e32 v83, 1.0, v83
	v_cvt_f32_i32_e32 v77, v37
	v_cvt_f32_i32_e32 v76, v36
	v_cvt_f32_i32_e32 v79, v35
	v_cvt_f32_i32_e32 v78, v34
	v_add_f32_e32 v97, 1.0, v97
	v_rcp_f32_e32 v198, v188
	v_rcp_f32_e32 v199, v83
	v_rcp_f32_e32 v97, v97
	v_pk_mul_f32 v[76:77], v[194:195], v[76:77] op_sel_hi:[0,1]
	v_pk_mul_f32 v[78:79], v[194:195], v[78:79] op_sel_hi:[0,1]
	v_pk_fma_f32 v[76:77], v[76:77], v[58:59], v[68:69] neg_lo:[1,0,0] neg_hi:[1,0,0]
	v_pk_mul_f32 v[56:57], v[56:57], v[198:199]
	v_pk_fma_f32 v[78:79], v[78:79], v[60:61], v[70:71] neg_lo:[1,0,0] neg_hi:[1,0,0]
	v_pk_mul_f32 v[66:67], v[66:67], v[96:97]
	v_pk_mul_f32 v[56:57], v[76:77], v[56:57]
	v_pk_mul_f32 v[66:67], v[78:79], v[66:67]
	v_max3_f32 v82, v226, 0, v82
	v_cvt_pk_bf16_f32 v76, v66, v67
	v_cvt_pk_bf16_f32 v77, v56, v57
	v_max_f32_e64 v56, |v56|, |v57|
	v_max3_f32 v78, |v66|, |v67|, v56
	v_cvt_f32_i32_e32 v67, v31
	v_cvt_f32_i32_e32 v66, v30
	v_cvt_f32_i32_e32 v57, v33
	v_cvt_f32_i32_e32 v56, v32
	global_store_dwordx4 v[80:81], v[74:77], off offset:2048
	v_pk_mul_f32 v[66:67], v[134:135], v[66:67] op_sel_hi:[0,1]
	v_pk_fma_f32 v[66:67], v[66:67], v[192:193], v[190:191] neg_lo:[1,0,0] neg_hi:[1,0,0]
	v_pk_mul_f32 v[56:57], v[134:135], v[56:57] op_sel_hi:[0,1]
	v_exp_f32_e32 v79, v66
	v_pk_fma_f32 v[56:57], v[56:57], v[62:63], v[72:73] neg_lo:[1,0,0] neg_hi:[1,0,0]
	v_exp_f32_e32 v81, v67
	v_exp_f32_e32 v83, v56
	v_add_f32_e32 v79, 1.0, v79
	v_rcp_f32_e32 v80, v79
	v_exp_f32_e32 v79, v57
	v_cvt_f32_i32_e32 v75, v29
	v_cvt_f32_i32_e32 v77, v27
	v_cvt_f32_i32_e32 v76, v26
	v_cvt_f32_i32_e32 v74, v28
	v_add_f32_e32 v81, 1.0, v81
	v_add_f32_e32 v83, 1.0, v83
	v_add_f32_e32 v79, 1.0, v79
	v_rcp_f32_e32 v96, v83
	v_rcp_f32_e32 v97, v79
	v_rcp_f32_e32 v81, v81
	v_pk_mul_f32 v[76:77], v[134:135], v[76:77] op_sel_hi:[0,1]
	v_pk_mul_f32 v[74:75], v[134:135], v[74:75] op_sel_hi:[0,1]
	v_pk_fma_f32 v[74:75], v[74:75], v[58:59], v[68:69] neg_lo:[1,0,0] neg_hi:[1,0,0]
	v_pk_fma_f32 v[76:77], v[76:77], v[60:61], v[70:71] neg_lo:[1,0,0] neg_hi:[1,0,0]
	v_pk_mul_f32 v[56:57], v[56:57], v[96:97]
	v_pk_mul_f32 v[66:67], v[66:67], v[80:81]
	v_pk_mul_f32 v[56:57], v[74:75], v[56:57]
	v_pk_mul_f32 v[74:75], v[76:77], v[66:67]
	v_cvt_f32_i32_e32 v77, v23
	v_cvt_f32_i32_e32 v76, v22
	v_cvt_pk_bf16_f32 v66, v74, v75
	v_cvt_pk_bf16_f32 v67, v56, v57
	v_max_f32_e64 v56, |v56|, |v57|
	v_max3_f32 v74, |v74|, |v75|, v56
	v_cvt_f32_i32_e32 v57, v25
	v_cvt_f32_i32_e32 v56, v24
	global_store_dwordx4 v[94:95], v[64:67], off
	v_max3_f32 v0, v227, 0, v0
	v_max3_f32 v78, v228, 0, v78
	v_pk_mul_f32 v[64:65], v[186:187], v[76:77] op_sel_hi:[0,1]
	v_pk_fma_f32 v[64:65], v[64:65], v[192:193], v[190:191] neg_lo:[1,0,0] neg_hi:[1,0,0]
	v_pk_mul_f32 v[56:57], v[186:187], v[56:57] op_sel_hi:[0,1]
	v_exp_f32_e32 v75, v64
	v_pk_fma_f32 v[56:57], v[56:57], v[62:63], v[72:73] neg_lo:[1,0,0] neg_hi:[1,0,0]
	v_exp_f32_e32 v79, v65
	v_exp_f32_e32 v81, v56
	v_add_f32_e32 v75, 1.0, v75
	v_rcp_f32_e32 v80, v75
	v_exp_f32_e32 v75, v57
	v_cvt_f32_i32_e32 v77, v19
	v_cvt_f32_i32_e32 v76, v18
	v_add_f32_e32 v79, 1.0, v79
	v_add_f32_e32 v81, 1.0, v81
	v_rcp_f32_e32 v96, v81
	v_rcp_f32_e32 v81, v79
	v_cvt_f32_i32_e32 v67, v21
	v_cvt_f32_i32_e32 v66, v20
	v_add_f32_e32 v75, 1.0, v75
	v_pk_mul_f32 v[76:77], v[186:187], v[76:77] op_sel_hi:[0,1]
	v_rcp_f32_e32 v97, v75
	v_pk_fma_f32 v[76:77], v[76:77], v[60:61], v[70:71] neg_lo:[1,0,0] neg_hi:[1,0,0]
	v_pk_mul_f32 v[64:65], v[64:65], v[80:81]
	v_pk_mul_f32 v[66:67], v[186:187], v[66:67] op_sel_hi:[0,1]
	v_pk_mul_f32 v[64:65], v[76:77], v[64:65]
	v_cvt_f32_i32_e32 v77, v15
	v_cvt_f32_i32_e32 v76, v14
	v_pk_fma_f32 v[66:67], v[66:67], v[58:59], v[68:69] neg_lo:[1,0,0] neg_hi:[1,0,0]
	v_pk_mul_f32 v[56:57], v[56:57], v[96:97]
	v_max3_f32 v74, v220, 0, v74
	v_pk_mul_f32 v[66:67], v[66:67], v[56:57]
	v_cvt_pk_bf16_f32 v56, v64, v65
	s_mov_b64 s[28:29], 0
	v_cvt_pk_bf16_f32 v57, v66, v67
	v_max_f32_e64 v66, |v66|, |v67|
	global_store_dwordx4 v[94:95], v[54:57], off offset:2048
;     __device__ __forceinline__ void operator()(const f32x4 (&acc)[2][2][4][2], const Unit& u, int wr, int wc, int fr_, int fq_, LAS unsigned char* lds) const {
;     ...
;         float* hmx = (f8 & 4) ? (float*)((char*)out + (WS_HMX - WS_HID)) : nullptr;
;         if (F8_MASK != 0 && f8 == 1) EPI8_BODY(1);
;         else if (I8_MASK != 0 && f8 == 2) EPI8_BODY(2);
;         else EPI8_BODY(0);
	v_max3_f32 v64, |v64|, |v65|, v66
	v_cvt_f32_i32_e32 v67, v17
	v_pk_mul_f32 v[54:55], v[132:133], v[76:77] op_sel_hi:[0,1]
	v_cvt_f32_i32_e32 v66, v16
	v_pk_fma_f32 v[54:55], v[54:55], v[192:193], v[190:191] neg_lo:[1,0,0] neg_hi:[1,0,0]
	v_cvt_f32_i32_e32 v77, v11
	v_exp_f32_e32 v65, v54
	v_pk_mul_f32 v[56:57], v[132:133], v[66:67] op_sel_hi:[0,1]
	v_pk_fma_f32 v[56:57], v[56:57], v[62:63], v[72:73] neg_lo:[1,0,0] neg_hi:[1,0,0]
	v_exp_f32_e32 v75, v55
	v_add_f32_e32 v65, 1.0, v65
	v_exp_f32_e32 v79, v56
	v_rcp_f32_e32 v80, v65
	v_exp_f32_e32 v65, v57
	v_cvt_f32_i32_e32 v67, v13
	v_cvt_f32_i32_e32 v76, v10
	v_cvt_f32_i32_e32 v66, v12
	v_add_f32_e32 v75, 1.0, v75
	v_add_f32_e32 v79, 1.0, v79
	v_add_f32_e32 v65, 1.0, v65
	v_rcp_f32_e32 v96, v79
	v_rcp_f32_e32 v97, v65
	v_rcp_f32_e32 v81, v75
	v_pk_mul_f32 v[76:77], v[132:133], v[76:77] op_sel_hi:[0,1]
	v_pk_mul_f32 v[66:67], v[132:133], v[66:67] op_sel_hi:[0,1]
	v_pk_fma_f32 v[66:67], v[66:67], v[58:59], v[68:69] neg_lo:[1,0,0] neg_hi:[1,0,0]
	v_pk_fma_f32 v[76:77], v[76:77], v[60:61], v[70:71] neg_lo:[1,0,0] neg_hi:[1,0,0]
	v_pk_mul_f32 v[56:57], v[56:57], v[96:97]
	v_pk_mul_f32 v[54:55], v[54:55], v[80:81]
	v_pk_mul_f32 v[56:57], v[66:67], v[56:57]
	v_pk_mul_f32 v[66:67], v[76:77], v[54:55]
	v_cvt_f32_i32_e32 v77, v3
	v_cvt_f32_i32_e32 v76, v2
	v_add_co_u32_e32 v80, vcc, s14, v94
	v_cvt_pk_bf16_f32 v54, v66, v67
	v_cvt_pk_bf16_f32 v55, v56, v57
	v_max_f32_e64 v56, |v56|, |v57|
	s_nop 0
	v_addc_co_u32_e32 v81, vcc, 0, v95, vcc
	global_store_dwordx4 v[80:81], v[52:55], off
	v_max3_f32 v56, |v66|, |v67|, v56
	v_cvt_f32_i32_e32 v67, v5
	v_pk_mul_f32 v[52:53], v[104:105], v[76:77] op_sel_hi:[0,1]
	v_cvt_f32_i32_e32 v66, v4
	v_pk_fma_f32 v[52:53], v[52:53], v[192:193], v[190:191] neg_lo:[1,0,0] neg_hi:[1,0,0]
	v_cvt_f32_i32_e32 v77, v7
	v_exp_f32_e32 v57, v52
	v_pk_mul_f32 v[54:55], v[104:105], v[66:67] op_sel_hi:[0,1]
	v_pk_fma_f32 v[54:55], v[54:55], v[62:63], v[72:73] neg_lo:[1,0,0] neg_hi:[1,0,0]
	v_exp_f32_e32 v63, v53
	v_add_f32_e32 v57, 1.0, v57
	v_exp_f32_e32 v65, v54
	v_rcp_f32_e32 v62, v57
	v_exp_f32_e32 v57, v55
	v_cvt_f32_i32_e32 v67, v9
	v_cvt_f32_i32_e32 v66, v8
	v_add_f32_e32 v65, 1.0, v65
	v_add_f32_e32 v57, 1.0, v57
	v_cvt_f32_i32_e32 v76, v6
	v_add_f32_e32 v63, 1.0, v63
	v_rcp_f32_e32 v72, v65
	v_rcp_f32_e32 v73, v57
	v_rcp_f32_e32 v63, v63
	v_pk_mul_f32 v[66:67], v[104:105], v[66:67] op_sel_hi:[0,1]
	v_pk_mul_f32 v[76:77], v[104:105], v[76:77] op_sel_hi:[0,1]
	v_pk_fma_f32 v[58:59], v[66:67], v[58:59], v[68:69] neg_lo:[1,0,0] neg_hi:[1,0,0]
	v_pk_mul_f32 v[54:55], v[54:55], v[72:73]
	v_pk_fma_f32 v[60:61], v[76:77], v[60:61], v[70:71] neg_lo:[1,0,0] neg_hi:[1,0,0]
	v_pk_mul_f32 v[52:53], v[52:53], v[62:63]
	v_pk_mul_f32 v[54:55], v[58:59], v[54:55]
	v_pk_mul_f32 v[58:59], v[60:61], v[52:53]
	v_max3_f32 v64, v219, 0, v64
	v_cvt_pk_bf16_f32 v52, v58, v59
	v_cvt_pk_bf16_f32 v53, v54, v55
	v_max_f32_e64 v54, |v54|, |v55|
	v_max3_f32 v54, |v58|, |v59|, v54
	v_max3_f32 v56, v218, 0, v56
	v_max3_f32 v54, v196, 0, v54
	global_store_dwordx4 v[80:81], v[50:53], off offset:2048
.LBB0_331:
	s_andn2_b64 vcc, exec, s[28:29]
	s_ashr_i32 s27, s26, 31
	s_cbranch_vccnz .LBB0_333
	v_mov_b64_e32 v[50:51], v[224:225]
	v_mov_b64_e32 v[52:53], v[226:227]
	v_mov_b64_e32 v[68:69], v[220:221]
	v_mov_b64_e32 v[70:71], v[222:223]
	v_mov_b64_e32 v[54:55], v[232:233]
	v_mov_b64_e32 v[56:57], v[234:235]
	v_mov_b64_e32 v[74:75], v[228:229]
	v_mov_b64_e32 v[76:77], v[230:231]
	v_mov_b64_e32 v[58:59], v[240:241]
	v_mov_b64_e32 v[60:61], v[242:243]
	v_mov_b64_e32 v[78:79], v[236:237]
	v_mov_b64_e32 v[80:81], v[238:239]
	v_mov_b64_e32 v[62:63], v[248:249]
	v_mov_b64_e32 v[64:65], v[250:251]
	v_mov_b64_e32 v[190:191], v[244:245]
	v_mov_b64_e32 v[192:193], v[246:247]
	s_add_u32 s14, s31, s26
	s_addc_u32 s15, s30, s27
	s_lshl_b64 s[14:15], s[14:15], 14
	v_readlane_b32 s16, v255, 26
	s_add_u32 s28, s16, s14
	v_readlane_b32 s14, v255, 28
	s_addc_u32 s29, s14, s15
	v_readlane_b32 s14, v255, 30
	s_mov_b32 s16, 0x3fb8aa3b
	s_mov_b32 s20, 0xc0317218
	v_or_b32_e32 v0, s14, v217
	s_mov_b32 s14, 0xbfb8aa3b
	v_add_u32_e32 v0, v0, v184
	v_xor_b32_e32 v0, v0, v185
	v_lshrrev_b32_e32 v185, 1, v185
	v_xor_b32_e32 v0, v0, v185
	s_mov_b32 s22, 0x40317218
	s_waitcnt lgkmcnt(0)
	v_pk_mul_f32 v[82:83], v[138:139], v[172:173] op_sel_hi:[0,1]
	v_pk_mul_f32 v[158:159], v[136:137], v[158:159] op_sel_hi:[0,1]
	v_pk_mul_f32 v[142:143], v[134:135], v[142:143] op_sel_hi:[0,1]
	v_pk_mul_f32 v[114:115], v[132:133], v[114:115] op_sel_hi:[0,1]
	v_pk_mul_f32 v[118:119], v[132:133], v[118:119] op_sel_hi:[0,1]
	v_pk_mul_f32 v[116:117], v[132:133], v[116:117] op_sel_hi:[0,1]
	v_pk_mul_f32 v[98:99], v[138:139], v[98:99] op_sel_hi:[0,1]
	v_pk_mul_f32 v[92:93], v[138:139], v[92:93] op_sel_hi:[0,1]
	v_cvt_f32_i32_e32 v47, v47
	v_cvt_f32_i32_e32 v46, v46
	v_lshl_add_u64 v[66:67], s[28:29], 0, v[0:1]
	v_cvt_f32_i32_e32 v49, v49
	v_cvt_f32_i32_e32 v48, v48
	v_pk_mul_f32 v[46:47], v[136:137], v[46:47] op_sel_hi:[0,1]
	v_cvt_f32_i32_e32 v43, v43
	v_cvt_f32_i32_e32 v42, v42
	v_pk_mul_f32 v[48:49], v[136:137], v[48:49] op_sel_hi:[0,1]
	v_cvt_f32_i32_e32 v45, v45
	v_cvt_f32_i32_e32 v44, v44
	v_pk_mul_f32 v[42:43], v[136:137], v[42:43] op_sel_hi:[0,1]
	v_cvt_f32_i32_e32 v39, v39
	v_cvt_f32_i32_e32 v38, v38
	v_pk_mul_f32 v[44:45], v[136:137], v[44:45] op_sel_hi:[0,1]
	v_cvt_f32_i32_e32 v41, v41
	v_cvt_f32_i32_e32 v40, v40
	v_cvt_f32_i32_e32 v35, v35
	v_cvt_f32_i32_e32 v34, v34
	v_cvt_f32_i32_e32 v37, v37
	v_cvt_f32_i32_e32 v36, v36
	v_cvt_f32_i32_e32 v31, v31
	v_cvt_f32_i32_e32 v30, v30
	v_cvt_f32_i32_e32 v33, v33
	v_cvt_f32_i32_e32 v32, v32
	v_cvt_f32_i32_e32 v27, v27
	v_pk_mul_f32 v[30:31], v[134:135], v[30:31] op_sel_hi:[0,1]
	v_cvt_f32_i32_e32 v26, v26
	v_pk_mul_f32 v[32:33], v[134:135], v[32:33] op_sel_hi:[0,1]
	v_cvt_f32_i32_e32 v29, v29
	v_cvt_f32_i32_e32 v28, v28
	v_pk_mul_f32 v[26:27], v[134:135], v[26:27] op_sel_hi:[0,1]
	v_cvt_f32_i32_e32 v23, v23
	v_cvt_f32_i32_e32 v22, v22
	v_pk_mul_f32 v[28:29], v[134:135], v[28:29] op_sel_hi:[0,1]
	v_cvt_f32_i32_e32 v25, v25
	v_cvt_f32_i32_e32 v24, v24
	v_cvt_f32_i32_e32 v19, v19
	v_cvt_f32_i32_e32 v18, v18
	v_cvt_f32_i32_e32 v21, v21
	v_cvt_f32_i32_e32 v20, v20
	v_cvt_f32_i32_e32 v15, v15
	v_cvt_f32_i32_e32 v14, v14
	v_cvt_f32_i32_e32 v17, v17
	v_cvt_f32_i32_e32 v16, v16
	v_cvt_f32_i32_e32 v11, v11
	v_pk_mul_f32 v[14:15], v[132:133], v[14:15] op_sel_hi:[0,1]
	v_cvt_f32_i32_e32 v10, v10
	v_pk_mul_f32 v[16:17], v[132:133], v[16:17] op_sel_hi:[0,1]
	v_cvt_f32_i32_e32 v13, v13
	v_pk_mul_f32 v[96:97], v[68:69], s[14:15] op_sel_hi:[1,0]
	v_pk_mul_f32 v[68:69], v[138:139], v[178:179] op_sel_hi:[0,1]
	v_pk_mul_f32 v[182:183], v[70:71], s[14:15] op_sel_hi:[1,0]
	v_pk_mul_f32 v[70:71], v[138:139], v[174:175] op_sel_hi:[0,1]
	v_pk_mul_f32 v[180:181], v[78:79], s[16:17] op_sel_hi:[1,0]
	v_pk_mul_f32 v[184:185], v[80:81], s[16:17] op_sel_hi:[1,0]
	v_pk_fma_f32 v[68:69], v[68:69], v[180:181], v[96:97] neg_lo:[1,0,0] neg_hi:[1,0,0]
	v_pk_fma_f32 v[70:71], v[70:71], v[184:185], v[182:183] neg_lo:[1,0,0] neg_hi:[1,0,0]
	v_exp_f32_e32 v94, v68
	v_exp_f32_e32 v95, v69
	v_exp_f32_e32 v104, v70
	v_exp_f32_e32 v105, v71
	v_add_f32_e32 v94, 1.0, v94
	v_add_f32_e32 v95, 1.0, v95
	v_rcp_f32_e32 v94, v94
	v_rcp_f32_e32 v95, v95
	v_add_f32_e32 v104, 1.0, v104
	v_add_f32_e32 v105, 1.0, v105
	v_rcp_f32_e32 v104, v104
	v_rcp_f32_e32 v105, v105
	v_pk_mul_f32 v[74:75], v[74:75], s[20:21] op_sel_hi:[1,0]
	v_pk_mul_f32 v[78:79], v[190:191], s[22:23] op_sel_hi:[1,0]
	v_pk_mul_f32 v[80:81], v[138:139], v[176:177] op_sel_hi:[0,1]
	v_pk_mul_f32 v[72:73], v[76:77], s[20:21] op_sel_hi:[1,0]
	v_pk_mul_f32 v[76:77], v[192:193], s[22:23] op_sel_hi:[1,0]
	v_pk_fma_f32 v[80:81], v[80:81], v[78:79], v[74:75] neg_lo:[1,0,0] neg_hi:[1,0,0]
	v_pk_mul_f32 v[68:69], v[68:69], v[94:95]
	v_pk_fma_f32 v[82:83], v[82:83], v[76:77], v[72:73] neg_lo:[1,0,0] neg_hi:[1,0,0]
	v_pk_mul_f32 v[70:71], v[70:71], v[104:105]
	v_pk_mul_f32 v[68:69], v[80:81], v[68:69]
	s_mov_b32 s15, 0xc3e00000
	v_pk_mul_f32 v[70:71], v[82:83], v[70:71]
	v_med3_f32 v68, v68, s15, v209
	v_med3_f32 v69, v69, s15, v209
	v_mov_b32_e32 v82, v1
	v_cvt_pk_fp8_f32 v82, v68, v69
	v_med3_f32 v70, v70, s15, v209
	v_med3_f32 v71, v71, s15, v209
	v_pk_fma_f32 v[142:143], v[142:143], v[76:77], v[72:73] neg_lo:[1,0,0] neg_hi:[1,0,0]
	v_cvt_pk_fp8_f32 v82, v70, v71 op_sel:[0,0,1]
	v_mov_b32_e32 v70, v139
	v_pk_mul_f32 v[68:69], v[70:71], v[168:169] op_sel_hi:[0,1]
	v_pk_fma_f32 v[68:69], v[68:69], v[180:181], v[96:97] neg_lo:[1,0,0] neg_hi:[1,0,0]
	v_pk_mul_f32 v[80:81], v[70:71], v[164:165] op_sel_hi:[0,1]
	v_pk_mul_f32 v[94:95], v[70:71], v[170:171] op_sel_hi:[0,1]
	v_pk_mul_f32 v[104:105], v[70:71], v[166:167] op_sel_hi:[0,1]
	v_exp_f32_e32 v71, v68
	v_pk_fma_f32 v[80:81], v[80:81], v[184:185], v[182:183] neg_lo:[1,0,0] neg_hi:[1,0,0]
	v_pk_fma_f32 v[94:95], v[94:95], v[78:79], v[74:75] neg_lo:[1,0,0] neg_hi:[1,0,0]
	v_pk_fma_f32 v[104:105], v[104:105], v[76:77], v[72:73] neg_lo:[1,0,0] neg_hi:[1,0,0]
	v_add_f32_e32 v71, 1.0, v71
	v_rcp_f32_e32 v164, v71
	v_exp_f32_e32 v71, v69
	v_pk_fma_f32 v[114:115], v[114:115], v[184:185], v[182:183] neg_lo:[1,0,0] neg_hi:[1,0,0]
	v_pk_fma_f32 v[116:117], v[116:117], v[76:77], v[72:73] neg_lo:[1,0,0] neg_hi:[1,0,0]
	v_pk_fma_f32 v[118:119], v[118:119], v[78:79], v[74:75] neg_lo:[1,0,0] neg_hi:[1,0,0]
	v_add_f32_e32 v71, 1.0, v71
	v_rcp_f32_e32 v165, v71
	v_exp_f32_e32 v71, v80
	v_pk_mul_f32 v[50:51], v[50:51], s[14:15] op_sel_hi:[1,0]
	v_pk_mul_f32 v[52:53], v[52:53], s[14:15] op_sel_hi:[1,0]
	v_pk_mul_f32 v[68:69], v[68:69], v[164:165]
	v_add_f32_e32 v71, 1.0, v71
	v_rcp_f32_e32 v166, v71
	v_exp_f32_e32 v71, v81
	v_pk_mul_f32 v[68:69], v[94:95], v[68:69]
	v_mov_b32_e32 v94, v1
	v_med3_f32 v68, v68, s15, v209
	v_add_f32_e32 v71, 1.0, v71
	v_rcp_f32_e32 v167, v71
	v_med3_f32 v69, v69, s15, v209
	v_cvt_pk_fp8_f32 v94, v68, v69
; __device__ __forceinline__ unsigned cvt_fp8x4(float a, float b, float c, float d) {
;     a = __builtin_amdgcn_fmed3f(a, -448.f, 448.f); b = __builtin_amdgcn_fmed3f(b, -448.f, 448.f); c = __builtin_amdgcn_fmed3f(c, -448.f, 448.f); d = __builtin_amdgcn_fmed3f(d, -448.f, 448.f);
;     int r = 0; r = __builtin_amdgcn_cvt_pk_fp8_f32(a, b, r, false); r = __builtin_amdgcn_cvt_pk_fp8_f32(c, d, r, true); return (unsigned)r; }
	v_pk_mul_f32 v[68:69], v[136:137], v[160:161] op_sel_hi:[0,1]
	v_pk_mul_f32 v[80:81], v[80:81], v[166:167]
	v_pk_fma_f32 v[68:69], v[68:69], v[78:79], v[74:75] neg_lo:[1,0,0] neg_hi:[1,0,0]
	v_pk_mul_f32 v[80:81], v[104:105], v[80:81]
	v_pk_mul_f32 v[104:105], v[136:137], v[162:163] op_sel_hi:[0,1]
	v_med3_f32 v71, v80, s15, v209
	v_med3_f32 v80, v81, s15, v209
	v_pk_fma_f32 v[104:105], v[104:105], v[180:181], v[96:97] neg_lo:[1,0,0] neg_hi:[1,0,0]
	v_cvt_pk_fp8_f32 v94, v71, v80 op_sel:[0,0,1]
	v_exp_f32_e32 v71, v104
	v_pk_mul_f32 v[80:81], v[136:137], v[156:157] op_sel_hi:[0,1]
	v_pk_fma_f32 v[156:157], v[158:159], v[184:185], v[182:183] neg_lo:[1,0,0] neg_hi:[1,0,0]
	v_pk_fma_f32 v[80:81], v[80:81], v[76:77], v[72:73] neg_lo:[1,0,0] neg_hi:[1,0,0]
	v_add_f32_e32 v71, 1.0, v71
	v_rcp_f32_e32 v158, v71
	v_exp_f32_e32 v71, v105
	v_mov_b32_e32 v95, v1
	v_cvt_f32_i32_e32 v12, v12
	v_pk_mul_f32 v[10:11], v[132:133], v[10:11] op_sel_hi:[0,1]
	v_add_f32_e32 v71, 1.0, v71
	v_rcp_f32_e32 v159, v71
	v_exp_f32_e32 v71, v156
	v_cvt_f32_i32_e32 v3, v3
	v_cvt_f32_i32_e32 v2, v2
	v_pk_mul_f32 v[104:105], v[104:105], v[158:159]
	v_add_f32_e32 v71, 1.0, v71
	v_rcp_f32_e32 v160, v71
	v_exp_f32_e32 v71, v157
	v_pk_mul_f32 v[68:69], v[68:69], v[104:105]
	v_mov_b32_e32 v158, v1
	v_med3_f32 v68, v68, s15, v209
	v_add_f32_e32 v71, 1.0, v71
	v_rcp_f32_e32 v161, v71
	v_med3_f32 v69, v69, s15, v209
	v_cvt_pk_fp8_f32 v158, v68, v69
	v_mov_b32_e32 v159, v1
	v_pk_mul_f32 v[156:157], v[156:157], v[160:161]
	v_pk_mul_f32 v[12:13], v[132:133], v[12:13] op_sel_hi:[0,1]
	v_pk_mul_f32 v[80:81], v[80:81], v[156:157]
	v_mov_b32_e32 v156, v137
	v_pk_mul_f32 v[68:69], v[156:157], v[154:155] op_sel_hi:[0,1]
	v_med3_f32 v71, v80, s15, v209
	v_med3_f32 v80, v81, s15, v209
	v_pk_fma_f32 v[68:69], v[68:69], v[180:181], v[96:97] neg_lo:[1,0,0] neg_hi:[1,0,0]
	v_cvt_pk_fp8_f32 v158, v71, v80 op_sel:[0,0,1]
	v_exp_f32_e32 v71, v68
	v_pk_mul_f32 v[80:81], v[156:157], v[148:149] op_sel_hi:[0,1]
	v_pk_mul_f32 v[148:149], v[156:157], v[150:151] op_sel_hi:[0,1]
	v_pk_fma_f32 v[80:81], v[80:81], v[184:185], v[182:183] neg_lo:[1,0,0] neg_hi:[1,0,0]
	v_add_f32_e32 v71, 1.0, v71
	v_rcp_f32_e32 v150, v71
	v_exp_f32_e32 v71, v69
	v_pk_mul_f32 v[104:105], v[156:157], v[152:153] op_sel_hi:[0,1]
	v_pk_fma_f32 v[104:105], v[104:105], v[78:79], v[74:75] neg_lo:[1,0,0] neg_hi:[1,0,0]
	v_pk_fma_f32 v[148:149], v[148:149], v[76:77], v[72:73] neg_lo:[1,0,0] neg_hi:[1,0,0]
	v_add_f32_e32 v71, 1.0, v71
	v_rcp_f32_e32 v151, v71
	v_exp_f32_e32 v71, v80
	v_pk_mul_f32 v[38:39], v[156:157], v[38:39] op_sel_hi:[0,1]
	v_pk_mul_f32 v[40:41], v[156:157], v[40:41] op_sel_hi:[0,1]
	v_pk_mul_f32 v[68:69], v[68:69], v[150:151]
	v_add_f32_e32 v71, 1.0, v71
	v_rcp_f32_e32 v152, v71
	v_exp_f32_e32 v71, v81
	v_pk_mul_f32 v[68:69], v[104:105], v[68:69]
	v_pk_mul_f32 v[104:105], v[134:135], v[140:141] op_sel_hi:[0,1]
	v_med3_f32 v68, v68, s15, v209
	v_add_f32_e32 v71, 1.0, v71
	v_rcp_f32_e32 v153, v71
	v_med3_f32 v69, v69, s15, v209
	v_pk_mul_f32 v[140:141], v[134:135], v[144:145] op_sel_hi:[0,1]
	v_pk_fma_f32 v[104:105], v[104:105], v[184:185], v[182:183] neg_lo:[1,0,0] neg_hi:[1,0,0]
	v_pk_mul_f32 v[80:81], v[80:81], v[152:153]
	v_pk_fma_f32 v[140:141], v[140:141], v[78:79], v[74:75] neg_lo:[1,0,0] neg_hi:[1,0,0]
	v_pk_mul_f32 v[80:81], v[148:149], v[80:81]
	v_mov_b32_e32 v148, v1
	v_cvt_pk_fp8_f32 v148, v68, v69
	v_med3_f32 v71, v80, s15, v209
	v_med3_f32 v80, v81, s15, v209
	v_pk_mul_f32 v[34:35], v[156:157], v[34:35] op_sel_hi:[0,1]
	v_cvt_pk_fp8_f32 v148, v71, v80 op_sel:[0,0,1]
	v_pk_mul_f32 v[80:81], v[134:135], v[146:147] op_sel_hi:[0,1]
	v_pk_fma_f32 v[80:81], v[80:81], v[180:181], v[96:97] neg_lo:[1,0,0] neg_hi:[1,0,0]
	v_mov_b32_e32 v149, v1
	v_exp_f32_e32 v71, v80
	v_pk_mul_f32 v[36:37], v[156:157], v[36:37] op_sel_hi:[0,1]
	v_cvt_f32_i32_e32 v5, v5
	v_cvt_f32_i32_e32 v4, v4
	v_add_f32_e32 v71, 1.0, v71
	v_rcp_f32_e32 v144, v71
	v_exp_f32_e32 v71, v81
	v_cvt_f32_i32_e32 v7, v7
	v_cvt_f32_i32_e32 v6, v6
	v_cvt_f32_i32_e32 v9, v9
	v_add_f32_e32 v71, 1.0, v71
	v_rcp_f32_e32 v145, v71
	v_exp_f32_e32 v71, v104
	v_cvt_f32_i32_e32 v8, v8
	s_movk_i32 s14, 0x1000
	v_pk_mul_f32 v[80:81], v[80:81], v[144:145]
	v_add_f32_e32 v71, 1.0, v71
	v_rcp_f32_e32 v146, v71
	v_exp_f32_e32 v71, v105
	v_pk_mul_f32 v[80:81], v[140:141], v[80:81]
	v_mov_b32_e32 v140, v1
	v_mov_b32_e32 v141, v1
	v_add_f32_e32 v71, 1.0, v71
	v_rcp_f32_e32 v147, v71
	v_med3_f32 v71, v80, s15, v209
	v_med3_f32 v80, v81, s15, v209
	v_cvt_pk_fp8_f32 v140, v71, v80
	v_pk_mul_f32 v[104:105], v[104:105], v[146:147]
	v_lshl_add_u64 v[68:69], v[66:67], 0, s[18:19]
	v_pk_mul_f32 v[104:105], v[142:143], v[104:105]
	s_nop 0
	v_med3_f32 v81, v104, s15, v209
	v_med3_f32 v83, v105, s15, v209
	v_mov_b32_e32 v104, v135
	v_cvt_pk_fp8_f32 v140, v81, v83 op_sel:[0,0,1]
	v_pk_mul_f32 v[80:81], v[104:105], v[128:129] op_sel_hi:[0,1]
	v_pk_fma_f32 v[80:81], v[80:81], v[180:181], v[96:97] neg_lo:[1,0,0] neg_hi:[1,0,0]
	v_pk_mul_f32 v[122:123], v[104:105], v[122:123] op_sel_hi:[0,1]
	v_exp_f32_e32 v71, v80
	v_pk_fma_f32 v[122:123], v[122:123], v[184:185], v[182:183] neg_lo:[1,0,0] neg_hi:[1,0,0]
	v_pk_mul_f32 v[126:127], v[104:105], v[126:127] op_sel_hi:[0,1]
	v_pk_mul_f32 v[124:125], v[104:105], v[124:125] op_sel_hi:[0,1]
	v_add_f32_e32 v71, 1.0, v71
	v_rcp_f32_e32 v128, v71
	v_exp_f32_e32 v71, v81
	v_pk_fma_f32 v[124:125], v[124:125], v[76:77], v[72:73] neg_lo:[1,0,0] neg_hi:[1,0,0]
	v_pk_fma_f32 v[126:127], v[126:127], v[78:79], v[74:75] neg_lo:[1,0,0] neg_hi:[1,0,0]
	v_pk_mul_f32 v[22:23], v[104:105], v[22:23] op_sel_hi:[0,1]
	v_add_f32_e32 v71, 1.0, v71
	v_rcp_f32_e32 v129, v71
; __device__ __forceinline__ unsigned cvt_fp8x4(float a, float b, float c, float d) {
;     a = __builtin_amdgcn_fmed3f(a, -448.f, 448.f); b = __builtin_amdgcn_fmed3f(b, -448.f, 448.f); c = __builtin_amdgcn_fmed3f(c, -448.f, 448.f); d = __builtin_amdgcn_fmed3f(d, -448.f, 448.f);
;     int r = 0; r = __builtin_amdgcn_cvt_pk_fp8_f32(a, b, r, false); r = __builtin_amdgcn_cvt_pk_fp8_f32(c, d, r, true); return (unsigned)r; }
	v_exp_f32_e32 v71, v122
	v_pk_mul_f32 v[24:25], v[104:105], v[24:25] op_sel_hi:[0,1]
	v_pk_mul_f32 v[18:19], v[104:105], v[18:19] op_sel_hi:[0,1]
	v_pk_mul_f32 v[80:81], v[80:81], v[128:129]
	v_add_f32_e32 v71, 1.0, v71
	v_rcp_f32_e32 v142, v71
	v_exp_f32_e32 v71, v123
	v_pk_mul_f32 v[80:81], v[126:127], v[80:81]
	v_pk_mul_f32 v[20:21], v[104:105], v[20:21] op_sel_hi:[0,1]
	v_mov_b32_e32 v105, 0
	v_add_f32_e32 v71, 1.0, v71
	v_rcp_f32_e32 v143, v71
	v_med3_f32 v71, v80, s15, v209
	v_med3_f32 v80, v81, s15, v209
	v_pk_mul_f32 v[122:123], v[122:123], v[142:143]
	s_nop 0
	v_pk_mul_f32 v[122:123], v[124:125], v[122:123]
	s_nop 0
	v_med3_f32 v81, v122, s15, v209
	v_mov_b32_e32 v122, v1
	v_cvt_pk_fp8_f32 v122, v71, v80
	v_med3_f32 v83, v123, s15, v209
	v_mov_b32_e32 v123, v1
	v_cvt_pk_fp8_f32 v122, v81, v83 op_sel:[0,0,1]
	v_pk_mul_f32 v[80:81], v[132:133], v[120:121] op_sel_hi:[0,1]
	v_pk_fma_f32 v[80:81], v[80:81], v[180:181], v[96:97] neg_lo:[1,0,0] neg_hi:[1,0,0]
	s_nop 0
	v_exp_f32_e32 v71, v80
	s_nop 0
	v_add_f32_e32 v71, 1.0, v71
	v_rcp_f32_e32 v120, v71
	v_exp_f32_e32 v71, v81
	s_nop 0
	v_add_f32_e32 v71, 1.0, v71
	v_rcp_f32_e32 v121, v71
	v_exp_f32_e32 v71, v114
	v_pk_mul_f32 v[80:81], v[80:81], v[120:121]
	v_add_f32_e32 v71, 1.0, v71
	v_rcp_f32_e32 v124, v71
	v_exp_f32_e32 v71, v115
	v_pk_mul_f32 v[80:81], v[118:119], v[80:81]
	v_add_f32_e32 v71, 1.0, v71
	v_rcp_f32_e32 v125, v71
	v_med3_f32 v71, v80, s15, v209
	v_med3_f32 v80, v81, s15, v209
	v_pk_mul_f32 v[114:115], v[114:115], v[124:125]
	s_nop 0
	v_pk_mul_f32 v[114:115], v[116:117], v[114:115]
	s_nop 0
	v_med3_f32 v81, v114, s15, v209
	v_mov_b32_e32 v114, v1
	v_cvt_pk_fp8_f32 v114, v71, v80
	v_mov_b32_e32 v80, v133
	v_pk_mul_f32 v[112:113], v[80:81], v[112:113] op_sel_hi:[0,1]
	v_pk_fma_f32 v[96:97], v[112:113], v[180:181], v[96:97] neg_lo:[1,0,0] neg_hi:[1,0,0]
	v_pk_mul_f32 v[106:107], v[80:81], v[106:107] op_sel_hi:[0,1]
	v_exp_f32_e32 v71, v96
	v_pk_fma_f32 v[106:107], v[106:107], v[184:185], v[182:183] neg_lo:[1,0,0] neg_hi:[1,0,0]
	v_pk_mul_f32 v[110:111], v[80:81], v[110:111] op_sel_hi:[0,1]
	v_pk_mul_f32 v[108:109], v[80:81], v[108:109] op_sel_hi:[0,1]
	v_add_f32_e32 v71, 1.0, v71
	v_rcp_f32_e32 v112, v71
	v_exp_f32_e32 v71, v97
	v_pk_fma_f32 v[72:73], v[108:109], v[76:77], v[72:73] neg_lo:[1,0,0] neg_hi:[1,0,0]
	v_pk_fma_f32 v[74:75], v[110:111], v[78:79], v[74:75] neg_lo:[1,0,0] neg_hi:[1,0,0]
	v_med3_f32 v83, v115, s15, v209
	v_add_f32_e32 v71, 1.0, v71
	v_rcp_f32_e32 v113, v71
	v_exp_f32_e32 v71, v106
	v_cvt_pk_fp8_f32 v114, v81, v83 op_sel:[0,0,1]
	v_mov_b32_e32 v83, v1
	v_pk_mul_f32 v[78:79], v[96:97], v[112:113]
	v_add_f32_e32 v71, 1.0, v71
	v_rcp_f32_e32 v116, v71
	v_exp_f32_e32 v71, v107
	v_pk_mul_f32 v[74:75], v[74:75], v[78:79]
	v_mov_b32_e32 v115, v1
	v_pk_mul_f32 v[2:3], v[80:81], v[2:3] op_sel_hi:[0,1]
	v_add_f32_e32 v71, 1.0, v71
	v_rcp_f32_e32 v117, v71
	v_med3_f32 v71, v74, s15, v209
	v_med3_f32 v74, v75, s15, v209
	v_pk_mul_f32 v[4:5], v[80:81], v[4:5] op_sel_hi:[0,1]
	v_pk_mul_f32 v[76:77], v[106:107], v[116:117]
	v_pk_mul_f32 v[6:7], v[80:81], v[6:7] op_sel_hi:[0,1]
	v_pk_mul_f32 v[72:73], v[72:73], v[76:77]
	v_pk_mul_f32 v[76:77], v[54:55], s[20:21] op_sel_hi:[1,0]
	v_med3_f32 v75, v72, s15, v209
	v_mov_b32_e32 v72, v1
	v_cvt_pk_fp8_f32 v72, v71, v74
	v_med3_f32 v73, v73, s15, v209
	v_pk_mul_f32 v[54:55], v[58:59], s[16:17] op_sel_hi:[1,0]
	v_pk_mul_f32 v[58:59], v[64:65], s[22:23] op_sel_hi:[1,0]
	v_cvt_pk_fp8_f32 v72, v75, v73 op_sel:[0,0,1]
	v_pk_mul_f32 v[74:75], v[56:57], s[20:21] op_sel_hi:[1,0]
	v_pk_mul_f32 v[56:57], v[60:61], s[16:17] op_sel_hi:[1,0]
	v_pk_mul_f32 v[60:61], v[62:63], s[22:23] op_sel_hi:[1,0]
	v_pk_mul_f32 v[62:63], v[138:139], v[102:103] op_sel_hi:[0,1]
	v_pk_fma_f32 v[62:63], v[62:63], v[54:55], v[50:51] neg_lo:[1,0,0] neg_hi:[1,0,0]
	v_pk_mul_f32 v[64:65], v[138:139], v[100:101] op_sel_hi:[0,1]
	v_exp_f32_e32 v71, v62
	v_pk_fma_f32 v[64:65], v[64:65], v[56:57], v[52:53] neg_lo:[1,0,0] neg_hi:[1,0,0]
	v_pk_fma_f32 v[98:99], v[98:99], v[60:61], v[76:77] neg_lo:[1,0,0] neg_hi:[1,0,0]
	v_pk_fma_f32 v[92:93], v[92:93], v[58:59], v[74:75] neg_lo:[1,0,0] neg_hi:[1,0,0]
	v_add_f32_e32 v71, 1.0, v71
	v_rcp_f32_e32 v78, v71
	v_exp_f32_e32 v71, v63
	v_pk_fma_f32 v[46:47], v[46:47], v[54:55], v[50:51] neg_lo:[1,0,0] neg_hi:[1,0,0]
	v_pk_fma_f32 v[48:49], v[48:49], v[56:57], v[52:53] neg_lo:[1,0,0] neg_hi:[1,0,0]
	v_pk_fma_f32 v[42:43], v[42:43], v[60:61], v[76:77] neg_lo:[1,0,0] neg_hi:[1,0,0]
	v_add_f32_e32 v71, 1.0, v71
	v_rcp_f32_e32 v79, v71
	v_exp_f32_e32 v71, v64
	v_pk_fma_f32 v[44:45], v[44:45], v[58:59], v[74:75] neg_lo:[1,0,0] neg_hi:[1,0,0]
	v_pk_fma_f32 v[38:39], v[38:39], v[54:55], v[50:51] neg_lo:[1,0,0] neg_hi:[1,0,0]
	v_pk_mul_f32 v[62:63], v[62:63], v[78:79]
	v_add_f32_e32 v71, 1.0, v71
	v_rcp_f32_e32 v96, v71
	v_exp_f32_e32 v71, v65
	v_pk_mul_f32 v[62:63], v[98:99], v[62:63]
	v_pk_fma_f32 v[40:41], v[40:41], v[56:57], v[52:53] neg_lo:[1,0,0] neg_hi:[1,0,0]
	v_med3_f32 v62, v62, s15, v209
	v_add_f32_e32 v71, 1.0, v71
	v_rcp_f32_e32 v97, v71
	v_med3_f32 v63, v63, s15, v209
	v_cvt_pk_fp8_f32 v83, v62, v63
	v_pk_mul_f32 v[62:63], v[70:71], v[90:91] op_sel_hi:[0,1]
	v_pk_mul_f32 v[64:65], v[64:65], v[96:97]
	v_pk_fma_f32 v[62:63], v[62:63], v[54:55], v[50:51] neg_lo:[1,0,0] neg_hi:[1,0,0]
	v_pk_mul_f32 v[64:65], v[92:93], v[64:65]
	v_pk_fma_f32 v[34:35], v[34:35], v[60:61], v[76:77] neg_lo:[1,0,0] neg_hi:[1,0,0]
	v_med3_f32 v64, v64, s15, v209
	v_med3_f32 v65, v65, s15, v209
	v_cvt_pk_fp8_f32 v83, v64, v65 op_sel:[0,0,1]
	v_pk_mul_f32 v[64:65], v[70:71], v[88:89] op_sel_hi:[0,1]
	v_exp_f32_e32 v71, v62
; __device__ __forceinline__ unsigned cvt_fp8x4(float a, float b, float c, float d) {
;     a = __builtin_amdgcn_fmed3f(a, -448.f, 448.f); b = __builtin_amdgcn_fmed3f(b, -448.f, 448.f); c = __builtin_amdgcn_fmed3f(c, -448.f, 448.f); d = __builtin_amdgcn_fmed3f(d, -448.f, 448.f);
;     int r = 0; r = __builtin_amdgcn_cvt_pk_fp8_f32(a, b, r, false); r = __builtin_amdgcn_cvt_pk_fp8_f32(c, d, r, true); return (unsigned)r; }
	v_pk_fma_f32 v[64:65], v[64:65], v[56:57], v[52:53] neg_lo:[1,0,0] neg_hi:[1,0,0]
	global_store_dwordx2 v0, v[82:83], s[28:29]
	v_pk_fma_f32 v[36:37], v[36:37], v[58:59], v[74:75] neg_lo:[1,0,0] neg_hi:[1,0,0]
	v_add_f32_e32 v71, 1.0, v71
	v_rcp_f32_e32 v78, v71
	v_exp_f32_e32 v71, v63
	v_pk_fma_f32 v[30:31], v[30:31], v[54:55], v[50:51] neg_lo:[1,0,0] neg_hi:[1,0,0]
	v_pk_fma_f32 v[32:33], v[32:33], v[56:57], v[52:53] neg_lo:[1,0,0] neg_hi:[1,0,0]
	v_pk_fma_f32 v[26:27], v[26:27], v[60:61], v[76:77] neg_lo:[1,0,0] neg_hi:[1,0,0]
	v_add_f32_e32 v71, 1.0, v71
	v_rcp_f32_e32 v79, v71
	v_exp_f32_e32 v71, v64
	v_pk_fma_f32 v[28:29], v[28:29], v[58:59], v[74:75] neg_lo:[1,0,0] neg_hi:[1,0,0]
	v_pk_fma_f32 v[22:23], v[22:23], v[54:55], v[50:51] neg_lo:[1,0,0] neg_hi:[1,0,0]
	v_pk_mul_f32 v[62:63], v[62:63], v[78:79]
	v_add_f32_e32 v71, 1.0, v71
	v_rcp_f32_e32 v82, v71
	v_exp_f32_e32 v71, v65
	v_pk_fma_f32 v[24:25], v[24:25], v[56:57], v[52:53] neg_lo:[1,0,0] neg_hi:[1,0,0]
	v_pk_fma_f32 v[18:19], v[18:19], v[60:61], v[76:77] neg_lo:[1,0,0] neg_hi:[1,0,0]
	v_pk_fma_f32 v[20:21], v[20:21], v[58:59], v[74:75] neg_lo:[1,0,0] neg_hi:[1,0,0]
	v_add_f32_e32 v71, 1.0, v71
	v_pk_mul_f32 v[86:87], v[70:71], v[86:87] op_sel_hi:[0,1]
	v_rcp_f32_e32 v83, v71
	v_pk_mul_f32 v[70:71], v[70:71], v[84:85] op_sel_hi:[0,1]
	v_pk_fma_f32 v[84:85], v[86:87], v[60:61], v[76:77] neg_lo:[1,0,0] neg_hi:[1,0,0]
	v_pk_fma_f32 v[70:71], v[70:71], v[58:59], v[74:75] neg_lo:[1,0,0] neg_hi:[1,0,0]
	v_pk_mul_f32 v[62:63], v[84:85], v[62:63]
	v_pk_mul_f32 v[64:65], v[64:65], v[82:83]
	v_med3_f32 v62, v62, s15, v209
	v_med3_f32 v63, v63, s15, v209
	v_cvt_pk_fp8_f32 v95, v62, v63
	v_pk_mul_f32 v[64:65], v[70:71], v[64:65]
	v_pk_fma_f32 v[14:15], v[14:15], v[54:55], v[50:51] neg_lo:[1,0,0] neg_hi:[1,0,0]
	v_med3_f32 v64, v64, s15, v209
	v_med3_f32 v65, v65, s15, v209
	v_cvt_pk_fp8_f32 v95, v64, v65 op_sel:[0,0,1]
	v_pk_fma_f32 v[16:17], v[16:17], v[56:57], v[52:53] neg_lo:[1,0,0] neg_hi:[1,0,0]
	v_pk_fma_f32 v[10:11], v[10:11], v[60:61], v[76:77] neg_lo:[1,0,0] neg_hi:[1,0,0]
	v_pk_fma_f32 v[12:13], v[12:13], v[58:59], v[74:75] neg_lo:[1,0,0] neg_hi:[1,0,0]
	global_store_dwordx2 v0, v[94:95], s[28:29] offset:2048
	v_exp_f32_e32 v0, v46
	v_pk_fma_f32 v[2:3], v[2:3], v[54:55], v[50:51] neg_lo:[1,0,0] neg_hi:[1,0,0]
	v_pk_fma_f32 v[4:5], v[4:5], v[56:57], v[52:53] neg_lo:[1,0,0] neg_hi:[1,0,0]
	v_pk_fma_f32 v[6:7], v[6:7], v[60:61], v[76:77] neg_lo:[1,0,0] neg_hi:[1,0,0]
	v_add_f32_e32 v0, 1.0, v0
	v_rcp_f32_e32 v62, v0
	v_exp_f32_e32 v0, v47
	v_mov_b32_e32 v73, v1
	v_pk_mul_f32 v[8:9], v[80:81], v[8:9] op_sel_hi:[0,1]
	v_pk_fma_f32 v[8:9], v[8:9], v[58:59], v[74:75] neg_lo:[1,0,0] neg_hi:[1,0,0]
	v_add_f32_e32 v0, 1.0, v0
	v_rcp_f32_e32 v63, v0
	v_exp_f32_e32 v0, v48
	v_mov_b32_e32 v74, 0
	v_mov_b32_e32 v56, 0
	v_pk_mul_f32 v[46:47], v[46:47], v[62:63]
	v_add_f32_e32 v0, 1.0, v0
	v_rcp_f32_e32 v64, v0
	v_exp_f32_e32 v0, v49
	v_pk_mul_f32 v[42:43], v[42:43], v[46:47]
	v_mov_b32_e32 v54, 0
	v_med3_f32 v42, v42, s15, v209
	v_add_f32_e32 v0, 1.0, v0
	v_rcp_f32_e32 v65, v0
	v_med3_f32 v43, v43, s15, v209
	v_cvt_pk_fp8_f32 v159, v42, v43
	v_add_co_u32_e32 v42, vcc, s14, v66
	v_pk_mul_f32 v[48:49], v[48:49], v[64:65]
	s_nop 0
	v_addc_co_u32_e32 v43, vcc, 0, v67, vcc
	v_pk_mul_f32 v[44:45], v[44:45], v[48:49]
	v_mov_b32_e32 v64, 0
	v_med3_f32 v0, v44, s15, v209
	v_med3_f32 v44, v45, s15, v209
	v_cvt_pk_fp8_f32 v159, v0, v44 op_sel:[0,0,1]
	v_exp_f32_e32 v0, v38
	v_mov_b32_e32 v82, 0
	v_mov_b32_e32 v78, 0
	global_store_dwordx2 v[42:43], v[158:159], off
	v_add_f32_e32 v0, 1.0, v0
	v_rcp_f32_e32 v44, v0
	v_exp_f32_e32 v0, v39
	s_nop 0
	v_add_f32_e32 v0, 1.0, v0
; __device__ __forceinline__ unsigned cvt_fp8x4(float a, float b, float c, float d) {
;     a = __builtin_amdgcn_fmed3f(a, -448.f, 448.f); b = __builtin_amdgcn_fmed3f(b, -448.f, 448.f); c = __builtin_amdgcn_fmed3f(c, -448.f, 448.f); d = __builtin_amdgcn_fmed3f(d, -448.f, 448.f);
;     int r = 0; r = __builtin_amdgcn_cvt_pk_fp8_f32(a, b, r, false); r = __builtin_amdgcn_cvt_pk_fp8_f32(c, d, r, true); return (unsigned)r; }
	v_rcp_f32_e32 v45, v0
	v_exp_f32_e32 v0, v40
	v_pk_mul_f32 v[38:39], v[38:39], v[44:45]
	v_add_f32_e32 v0, 1.0, v0
	v_rcp_f32_e32 v46, v0
	v_exp_f32_e32 v0, v41
	v_pk_mul_f32 v[34:35], v[34:35], v[38:39]
	v_add_f32_e32 v0, 1.0, v0
	v_rcp_f32_e32 v47, v0
	v_med3_f32 v34, v34, s15, v209
	v_med3_f32 v35, v35, s15, v209
	v_cvt_pk_fp8_f32 v149, v34, v35
	v_pk_mul_f32 v[40:41], v[40:41], v[46:47]
	s_nop 0
	v_pk_mul_f32 v[36:37], v[36:37], v[40:41]
	s_nop 0
	v_med3_f32 v0, v36, s15, v209
	v_med3_f32 v36, v37, s15, v209
	v_cvt_pk_fp8_f32 v149, v0, v36 op_sel:[0,0,1]
	v_exp_f32_e32 v0, v30
	global_store_dwordx2 v[42:43], v[148:149], off offset:2048
	v_add_f32_e32 v0, 1.0, v0
	v_rcp_f32_e32 v34, v0
	v_exp_f32_e32 v0, v31
	s_nop 0
	v_add_f32_e32 v0, 1.0, v0
	v_rcp_f32_e32 v35, v0
	v_exp_f32_e32 v0, v32
	v_pk_mul_f32 v[30:31], v[30:31], v[34:35]
	v_add_f32_e32 v0, 1.0, v0
	v_rcp_f32_e32 v36, v0
	v_exp_f32_e32 v0, v33
	v_pk_mul_f32 v[26:27], v[26:27], v[30:31]
	v_add_f32_e32 v0, 1.0, v0
	v_rcp_f32_e32 v37, v0
	v_med3_f32 v26, v26, s15, v209
	v_med3_f32 v27, v27, s15, v209
	v_cvt_pk_fp8_f32 v141, v26, v27
	v_pk_mul_f32 v[32:33], v[32:33], v[36:37]
	s_nop 0
	v_pk_mul_f32 v[28:29], v[28:29], v[32:33]
	s_nop 0
	v_med3_f32 v0, v28, s15, v209
	v_med3_f32 v28, v29, s15, v209
	v_cvt_pk_fp8_f32 v141, v0, v28 op_sel:[0,0,1]
	v_exp_f32_e32 v0, v22
	global_store_dwordx2 v[68:69], v[140:141], off
	v_add_f32_e32 v0, 1.0, v0
	v_rcp_f32_e32 v26, v0
	v_exp_f32_e32 v0, v23
	s_nop 0
	v_add_f32_e32 v0, 1.0, v0
	v_rcp_f32_e32 v27, v0
	v_exp_f32_e32 v0, v24
	v_pk_mul_f32 v[22:23], v[22:23], v[26:27]
	v_add_f32_e32 v0, 1.0, v0
	v_rcp_f32_e32 v28, v0
	v_exp_f32_e32 v0, v25
	v_pk_mul_f32 v[18:19], v[18:19], v[22:23]
	v_add_f32_e32 v0, 1.0, v0
	v_rcp_f32_e32 v29, v0
	v_med3_f32 v18, v18, s15, v209
	v_med3_f32 v19, v19, s15, v209
	v_cvt_pk_fp8_f32 v123, v18, v19
	v_pk_mul_f32 v[24:25], v[24:25], v[28:29]
	s_nop 0
	v_pk_mul_f32 v[20:21], v[20:21], v[24:25]
	s_nop 0
	v_med3_f32 v0, v20, s15, v209
	v_med3_f32 v20, v21, s15, v209
	v_cvt_pk_fp8_f32 v123, v0, v20 op_sel:[0,0,1]
	v_exp_f32_e32 v0, v14
	global_store_dwordx2 v[68:69], v[122:123], off offset:2048
	v_add_f32_e32 v0, 1.0, v0
	v_rcp_f32_e32 v18, v0
	v_exp_f32_e32 v0, v15
	s_nop 0
	v_add_f32_e32 v0, 1.0, v0
	v_rcp_f32_e32 v19, v0
	v_exp_f32_e32 v0, v16
	v_pk_mul_f32 v[14:15], v[14:15], v[18:19]
	v_add_f32_e32 v0, 1.0, v0
	v_rcp_f32_e32 v20, v0
	v_exp_f32_e32 v0, v17
	v_pk_mul_f32 v[10:11], v[10:11], v[14:15]
	v_add_f32_e32 v0, 1.0, v0
	v_rcp_f32_e32 v21, v0
	v_med3_f32 v10, v10, s15, v209
	v_med3_f32 v11, v11, s15, v209
	v_cvt_pk_fp8_f32 v115, v10, v11
	v_pk_mul_f32 v[16:17], v[16:17], v[20:21]
	v_add_co_u32_e32 v10, vcc, s14, v68
	v_pk_mul_f32 v[12:13], v[12:13], v[16:17]
	s_nop 0
	v_addc_co_u32_e32 v11, vcc, 0, v69, vcc
	v_med3_f32 v0, v12, s15, v209
	v_med3_f32 v12, v13, s15, v209
	v_cvt_pk_fp8_f32 v115, v0, v12 op_sel:[0,0,1]
	v_exp_f32_e32 v0, v2
	global_store_dwordx2 v[10:11], v[114:115], off
	v_add_f32_e32 v0, 1.0, v0
	v_rcp_f32_e32 v12, v0
	v_exp_f32_e32 v0, v3
	s_nop 0
	v_add_f32_e32 v0, 1.0, v0
	v_rcp_f32_e32 v13, v0
	v_exp_f32_e32 v0, v4
	v_pk_mul_f32 v[2:3], v[2:3], v[12:13]
	v_add_f32_e32 v0, 1.0, v0
	v_rcp_f32_e32 v14, v0
	v_exp_f32_e32 v0, v5
	v_pk_mul_f32 v[2:3], v[6:7], v[2:3]
	v_add_f32_e32 v0, 1.0, v0
	v_rcp_f32_e32 v15, v0
	v_med3_f32 v2, v2, s15, v209
	v_med3_f32 v3, v3, s15, v209
	v_cvt_pk_fp8_f32 v73, v2, v3
	v_pk_mul_f32 v[4:5], v[4:5], v[14:15]
	s_nop 0
	v_pk_mul_f32 v[4:5], v[8:9], v[4:5]
	s_nop 0
	v_med3_f32 v0, v4, s15, v209
	v_med3_f32 v4, v5, s15, v209
	v_cvt_pk_fp8_f32 v73, v0, v4 op_sel:[0,0,1]
	v_mov_b32_e32 v0, 0
	global_store_dwordx2 v[10:11], v[72:73], off offset:2048

; __device__ __forceinline__ unsigned xb_ld(unsigned* p)              { return __hip_atomic_load(p, __ATOMIC_RELAXED, __HIP_MEMORY_SCOPE_AGENT); }
; __device__ __forceinline__ unsigned xb_add(unsigned* p, unsigned v) { return __hip_atomic_fetch_add(p, v, __ATOMIC_RELAXED, __HIP_MEMORY_SCOPE_AGENT); }
; __device__ __forceinline__ void panel_barrier(unsigned* cnt, int tid) {
;     asm volatile("s_waitcnt vmcnt(0)" ::: "memory");
;     __syncthreads();
;     if (tid == 0) {
;         __builtin_amdgcn_s_waitcnt(0);
;         const unsigned old = xb_add(cnt, 1u), target = (old & ~3u) + 4u;
;         unsigned sp = 0u;
;         while (xb_ld(cnt) < target) { __builtin_amdgcn_s_sleep(1); if (++sp > (1u << 26)) break; }
;         __builtin_amdgcn_fence(__ATOMIC_ACQUIRE, "agent");
;         asm volatile("s_waitcnt vmcnt(0)" ::: "memory");
;     }
;     __syncthreads();
; }
.LBB0_427:
	s_and_b64 vcc, exec, s[4:5]
	s_cbranch_vccz .LBB0_443
	v_readlane_b32 s0, v254, 1
	v_mbcnt_lo_u32_b32 v0, -1, 0
	v_mbcnt_hi_u32_b32 v0, -1, v0
	s_nop 1
	v_lshl_add_u32 v0, s0, 6, v0
	s_waitcnt vmcnt(0)
	s_waitcnt vmcnt(0) lgkmcnt(0)
	v_cmp_eq_u32_e32 vcc, 0, v0
	s_barrier
	s_and_saveexec_b64 s[4:5], vcc
	s_cbranch_execz .LBB0_442
	v_readlane_b32 s0, v254, 19
	s_lshl_b32 s0, s0, 2
	s_add_u32 s1, s92, s0
	s_addc_u32 s2, s93, 0
	v_mov_b32_e32 v0, s1
	v_add_co_u32_e32 v2, vcc, 0x12000, v0
	v_mov_b32_e32 v0, s2
	s_nop 0
	v_addc_co_u32_e32 v3, vcc, 0, v0, vcc
	s_waitcnt vmcnt(0) expcnt(0) lgkmcnt(0)
	flat_atomic_add v[2:3], v210 offset:2048
	buffer_inv sc1
	s_add_u32 s6, s1, 0x12800
	s_mov_b32 s0, 0x4000001
	s_addc_u32 s7, s2, 0
	s_mov_b64 s[8:9], 0
	s_add_i32 s101, s101, 4
	v_mov_b32_e32 v0, s101
	s_branch .LBB0_435

; __device__ __forceinline__ unsigned xb_ld(unsigned* p)              { return __hip_atomic_load(p, __ATOMIC_RELAXED, __HIP_MEMORY_SCOPE_AGENT); }
; __device__ __forceinline__ void panel_barrier(unsigned* cnt, int tid) {
;     ...
;         unsigned sp = 0u;
;         while (xb_ld(cnt) < target) { __builtin_amdgcn_s_sleep(1); if (++sp > (1u << 26)) break; }
;         __builtin_amdgcn_fence(__ATOMIC_ACQUIRE, "agent");
;         asm volatile("s_waitcnt vmcnt(0)" ::: "memory");
.LBB0_435:
	v_mov_b64_e32 v[2:3], s[6:7]
	flat_load_dword v2, v[2:3] sc1
	s_or_b64 s[10:11], s[10:11], exec
	s_waitcnt vmcnt(0) lgkmcnt(0)
	v_cmp_lt_u32_e32 vcc, v2, v0
	s_and_saveexec_b64 s[12:13], vcc
	s_cbranch_execz .LBB0_434
	v_mov_b64_e32 v[2:3], s[6:7]
	s_sleep 1
	flat_load_dword v2, v[2:3] sc1
	s_mov_b64 s[16:17], -1
	s_waitcnt vmcnt(0) lgkmcnt(0)
	v_cmp_lt_u32_e32 vcc, v2, v0
	s_and_saveexec_b64 s[14:15], vcc
	s_cbranch_execz .LBB0_433
	v_mov_b64_e32 v[2:3], s[6:7]
	s_sleep 1
	flat_load_dword v2, v[2:3] sc1
	s_mov_b64 s[18:19], -1
	s_waitcnt vmcnt(0) lgkmcnt(0)
	v_cmp_lt_u32_e32 vcc, v2, v0
	s_and_saveexec_b64 s[16:17], vcc
	s_cbranch_execz .LBB0_432
	v_mov_b64_e32 v[2:3], s[6:7]
	s_sleep 1
	flat_load_dword v2, v[2:3] sc1
	s_mov_b64 s[20:21], -1
	s_waitcnt vmcnt(0) lgkmcnt(0)
	v_cmp_lt_u32_e32 vcc, v2, v0
	s_and_saveexec_b64 s[18:19], vcc
	s_cbranch_execz .LBB0_431
	v_mov_b64_e32 v[2:3], s[6:7]
	s_sleep 1
	flat_load_dword v2, v[2:3] sc1
	s_waitcnt vmcnt(0) lgkmcnt(0)
	v_cmp_lt_u32_e32 vcc, v2, v0
	s_and_saveexec_b64 s[22:23], vcc
	s_cbranch_execz .LBB0_430
	s_add_i32 s0, s0, -5
	s_cmp_eq_u32 s0, 0
	s_cselect_b64 s[2:3], -1, 0
	s_orn2_b64 s[20:21], s[2:3], exec
	s_sleep 1
	s_branch .LBB0_430
.LBB0_441:
	s_or_b64 exec, exec, s[8:9]
	s_waitcnt vmcnt(0)
.LBB0_442:
	s_or_b64 exec, exec, s[4:5]
	s_barrier

; __device__ __forceinline__ unsigned xb_ld(unsigned* p)              { return __hip_atomic_load(p, __ATOMIC_RELAXED, __HIP_MEMORY_SCOPE_AGENT); }
; __device__ __forceinline__ unsigned xb_add(unsigned* p, unsigned v) { return __hip_atomic_fetch_add(p, v, __ATOMIC_RELAXED, __HIP_MEMORY_SCOPE_AGENT); }
; __device__ __forceinline__ void panel_barrier(unsigned* cnt, int tid) {
;     asm volatile("s_waitcnt vmcnt(0)" ::: "memory");
;     __syncthreads();
;     if (tid == 0) {
;         __builtin_amdgcn_s_waitcnt(0);
;         const unsigned old = xb_add(cnt, 1u), target = (old & ~3u) + 4u;
;         unsigned sp = 0u;
;         while (xb_ld(cnt) < target) { __builtin_amdgcn_s_sleep(1); if (++sp > (1u << 26)) break; }
;         __builtin_amdgcn_fence(__ATOMIC_ACQUIRE, "agent");
;         asm volatile("s_waitcnt vmcnt(0)" ::: "memory");
;     }
;     __syncthreads();
; }
.LBB0_620:
	s_and_b64 vcc, exec, s[4:5]
	s_cbranch_vccz .LBB0_636
	v_readlane_b32 s0, v254, 1
	v_mbcnt_lo_u32_b32 v0, -1, 0
	v_mbcnt_hi_u32_b32 v0, -1, v0
	s_nop 1
	v_lshl_add_u32 v0, s0, 6, v0
	s_waitcnt vmcnt(0)
	s_nop 0
	v_cmp_eq_u32_e32 vcc, 0, v0
	s_barrier
	s_and_saveexec_b64 s[4:5], vcc
	s_cbranch_execz .LBB0_635
	v_readlane_b32 s0, v254, 54
	s_add_u32 s1, s92, s0
	s_addc_u32 s2, s93, 0
	v_mov_b32_e32 v0, s1
	v_add_co_u32_e32 v2, vcc, 0x12000, v0
	v_mov_b32_e32 v0, s2
	s_nop 0
	v_addc_co_u32_e32 v3, vcc, 0, v0, vcc
	s_waitcnt vmcnt(0) expcnt(0) lgkmcnt(0)
	flat_atomic_add v[2:3], v210 offset:2048
	buffer_inv sc1
	s_add_u32 s6, s1, 0x12800
	s_mov_b32 s0, 0x4000001
	s_addc_u32 s7, s2, 0
	s_mov_b64 s[8:9], 0
	s_add_i32 s101, s101, 4
	v_mov_b32_e32 v0, s101
	s_branch .LBB0_628

; __device__ __forceinline__ unsigned xb_ld(unsigned* p)              { return __hip_atomic_load(p, __ATOMIC_RELAXED, __HIP_MEMORY_SCOPE_AGENT); }
; __device__ __forceinline__ void panel_barrier(unsigned* cnt, int tid) {
;     ...
;         unsigned sp = 0u;
;         while (xb_ld(cnt) < target) { __builtin_amdgcn_s_sleep(1); if (++sp > (1u << 26)) break; }
;         __builtin_amdgcn_fence(__ATOMIC_ACQUIRE, "agent");
;         asm volatile("s_waitcnt vmcnt(0)" ::: "memory");
.LBB0_628:
	v_mov_b64_e32 v[2:3], s[6:7]
	flat_load_dword v2, v[2:3] sc1
	s_or_b64 s[10:11], s[10:11], exec
	s_waitcnt vmcnt(0) lgkmcnt(0)
	v_cmp_lt_u32_e32 vcc, v2, v0
	s_and_saveexec_b64 s[12:13], vcc
	s_cbranch_execz .LBB0_627
	v_mov_b64_e32 v[2:3], s[6:7]
	s_sleep 1
	flat_load_dword v2, v[2:3] sc1
	s_mov_b64 s[16:17], -1
	s_waitcnt vmcnt(0) lgkmcnt(0)
	v_cmp_lt_u32_e32 vcc, v2, v0
	s_and_saveexec_b64 s[14:15], vcc
	s_cbranch_execz .LBB0_626
	v_mov_b64_e32 v[2:3], s[6:7]
	s_sleep 1
	flat_load_dword v2, v[2:3] sc1
	s_mov_b64 s[18:19], -1
	s_waitcnt vmcnt(0) lgkmcnt(0)
	v_cmp_lt_u32_e32 vcc, v2, v0
	s_and_saveexec_b64 s[16:17], vcc
	s_cbranch_execz .LBB0_625
	v_mov_b64_e32 v[2:3], s[6:7]
	s_sleep 1
	flat_load_dword v2, v[2:3] sc1
	s_mov_b64 s[20:21], -1
	s_waitcnt vmcnt(0) lgkmcnt(0)
	v_cmp_lt_u32_e32 vcc, v2, v0
	s_and_saveexec_b64 s[18:19], vcc
	s_cbranch_execz .LBB0_624
	v_mov_b64_e32 v[2:3], s[6:7]
	s_sleep 1
	flat_load_dword v2, v[2:3] sc1
	s_waitcnt vmcnt(0) lgkmcnt(0)
	v_cmp_lt_u32_e32 vcc, v2, v0
	s_and_saveexec_b64 s[22:23], vcc
	s_cbranch_execz .LBB0_623
	s_add_i32 s0, s0, -5
	s_cmp_eq_u32 s0, 0
	s_cselect_b64 s[2:3], -1, 0
	s_orn2_b64 s[20:21], s[2:3], exec
	s_sleep 1
	s_branch .LBB0_623
.LBB0_634:
	s_or_b64 exec, exec, s[8:9]
	s_waitcnt vmcnt(0)
.LBB0_635:
	s_or_b64 exec, exec, s[4:5]
	s_barrier

; #define EPI_LOAD(t) do { _Pragma("unroll") for (int mm = 0; mm < 2; ++mm) _Pragma("unroll") for (int n = 0; n < 2; ++n) \
;             xr[(t) % 3][mm][n] = rm ? *(const GAS f32x4*)(xi + EPI_OFF(((t) >> 1) & 1, 2 * ((t) & 1) + mm, (t) >> 2, n) * 4 + lo4) : *(const GAS f32x4*)(xi + EPI_BLK(((t) >> 1) & 1, 2 * ((t) & 1) + mm, (t) >> 2, n) + lx); } while (0)
; #define EPI_FENCE() asm volatile("" ::: "memory")
;     __device__ __forceinline__ void operator()(const f32x4 (&acc)[2][2][4][2], const Unit& u, int wr, int wc, int fr_, int fq_, LAS unsigned char* lds) const {
;     ...
;         EPI_VEC(0); EPI_LOAD(0); EPI_FENCE(); EPI_LOAD(1); EPI_FENCE(); EPI_LOAD(2); EPI_FENCE();
;         EPI_DO(0); EPI_FENCE(); EPI_LOAD(3); EPI_FENCE();
;         EPI_DO(1); EPI_FENCE(); EPI_LOAD(4); EPI_FENCE();
;         EPI_DO(2); EPI_FENCE(); EPI_LOAD(5); EPI_FENCE();
;         EPI_DO(3); EPI_FENCE(); EPI_LOAD(6); EPI_FENCE();
;         EPI_VEC(1); EPI_FENCE();
.LBB0_681:
	s_lshr_b32 s10, s91, 4
	s_mulk_i32 s10, 0x4800
	s_add_u32 s8, s8, s10
	s_addc_u32 s9, s9, 0
	s_lshl_b64 s[8:9], s[8:9], 2
	v_readlane_b32 s10, v255, 14
	v_lshlrev_b32_e32 v130, 5, v196
	s_add_u32 s10, s10, s8
	v_readlane_b32 s11, v255, 15
	s_addc_u32 s11, s11, s9
	v_ashrrev_i32_e32 v131, 31, v130
	v_mov_b32_e32 v166, v198
	v_lshl_add_u64 v[168:169], s[10:11], 0, v[130:131]
	v_readlane_b32 s98, v255, 24
	s_add_u32 s98, s98, s8
	v_readlane_b32 s99, v255, 21
	s_addc_u32 s99, s99, s9
	v_lshl_add_u64 v[140:141], s[98:99], 0, v[130:131]
	v_readlane_b32 s98, v254, 62
	s_add_u32 s98, s98, s4
	v_readlane_b32 s99, v255, 9
	s_addc_u32 s99, s99, s5
	v_lshl_add_u64 v[142:143], s[98:99], 0, v[130:131]
	global_load_dword v144, v[168:169], off offset:512
	global_load_dword v145, v[140:141], off
	global_load_dword v146, v[140:141], off offset:512
	global_load_dword v147, v[142:143], off
	global_load_dword v148, v[142:143], off offset:512
	global_load_dwordx4 v[132:135], v[168:169], off
	s_add_u32 s66, s16, s4
	v_cndmask_b32_e64 v136, 0, 1, s[68:69]
	s_addc_u32 s67, s17, s5
	v_cmp_ne_u32_e64 s[10:11], 1, v136
	s_andn2_b64 vcc, exec, s[68:69]
	v_lshl_add_u64 v[170:171], s[66:67], 0, v[130:131]
	s_waitcnt vmcnt(0)
	v_pk_mul_f32 v[182:183], v[134:135], v[166:167] op_sel_hi:[1,0]
	v_pk_mul_f32 v[180:181], v[132:133], v[166:167] op_sel_hi:[1,0]
	s_cbranch_vccnz .LBB0_683
	global_load_dwordx4 v[132:135], v[170:171], off
	s_waitcnt vmcnt(0)
	v_pk_mul_f32 v[182:183], v[182:183], v[134:135]
	v_pk_mul_f32 v[180:181], v[180:181], v[132:133]

; #define EPI_LOAD(t) do { _Pragma("unroll") for (int mm = 0; mm < 2; ++mm) _Pragma("unroll") for (int n = 0; n < 2; ++n) \
;             xr[(t) % 3][mm][n] = rm ? *(const GAS f32x4*)(xi + EPI_OFF(((t) >> 1) & 1, 2 * ((t) & 1) + mm, (t) >> 2, n) * 4 + lo4) : *(const GAS f32x4*)(xi + EPI_BLK(((t) >> 1) & 1, 2 * ((t) & 1) + mm, (t) >> 2, n) + lx); } while (0)
; #define EPI_FENCE() asm volatile("" ::: "memory")
;     __device__ __forceinline__ void operator()(const f32x4 (&acc)[2][2][4][2], const Unit& u, int wr, int wc, int fr_, int fq_, LAS unsigned char* lds) const {
;     ...
;         EPI_VEC(0); EPI_LOAD(0); EPI_FENCE(); EPI_LOAD(1); EPI_FENCE(); EPI_LOAD(2); EPI_FENCE();
;         EPI_DO(0); EPI_FENCE(); EPI_LOAD(3); EPI_FENCE();
;         EPI_DO(1); EPI_FENCE(); EPI_LOAD(4); EPI_FENCE();
;         EPI_DO(2); EPI_FENCE(); EPI_LOAD(5); EPI_FENCE();
;         EPI_DO(3); EPI_FENCE(); EPI_LOAD(6); EPI_FENCE();
;         EPI_VEC(1); EPI_FENCE();
.LBB0_921:
	s_lshr_b32 s10, s87, 4
	s_mulk_i32 s10, 0x4800
	s_add_u32 s8, s8, s10
	s_addc_u32 s9, s9, 0
	s_lshl_b64 s[8:9], s[8:9], 2
	v_readlane_b32 s10, v255, 14
	v_lshlrev_b32_e32 v130, 5, v194
	s_add_u32 s10, s10, s8
	v_readlane_b32 s11, v255, 15
	s_addc_u32 s11, s11, s9
	v_ashrrev_i32_e32 v131, 31, v130
	v_mov_b32_e32 v164, v198
	v_lshl_add_u64 v[166:167], s[10:11], 0, v[130:131]
	v_readlane_b32 s98, v255, 24
	s_add_u32 s98, s98, s8
	v_readlane_b32 s99, v255, 21
	s_addc_u32 s99, s99, s9
	v_lshl_add_u64 v[140:141], s[98:99], 0, v[130:131]
	v_readlane_b32 s98, v254, 62
	s_add_u32 s98, s98, s4
	v_readlane_b32 s99, v255, 9
	s_addc_u32 s99, s99, s5
	v_lshl_add_u64 v[142:143], s[98:99], 0, v[130:131]
	global_load_dword v144, v[166:167], off offset:512
	global_load_dword v145, v[140:141], off
	global_load_dword v146, v[140:141], off offset:512
	global_load_dword v147, v[142:143], off
	global_load_dword v148, v[142:143], off offset:512
	global_load_dwordx4 v[132:135], v[166:167], off
	s_add_u32 s50, s16, s4
	v_cndmask_b32_e64 v136, 0, 1, s[66:67]
	s_addc_u32 s51, s17, s5
	v_cmp_ne_u32_e64 s[10:11], 1, v136
	s_andn2_b64 vcc, exec, s[66:67]
	v_lshl_add_u64 v[168:169], s[50:51], 0, v[130:131]
	s_waitcnt vmcnt(0)
	v_pk_mul_f32 v[180:181], v[134:135], v[164:165] op_sel_hi:[1,0]
	v_pk_mul_f32 v[178:179], v[132:133], v[164:165] op_sel_hi:[1,0]
	s_cbranch_vccnz .LBB0_923
	global_load_dwordx4 v[132:135], v[168:169], off
	s_waitcnt vmcnt(0)
	v_pk_mul_f32 v[180:181], v[180:181], v[134:135]
	v_pk_mul_f32 v[178:179], v[178:179], v[132:133]

; #define EPI_LOAD(t) do { _Pragma("unroll") for (int mm = 0; mm < 2; ++mm) _Pragma("unroll") for (int n = 0; n < 2; ++n) \
;             xr[(t) % 3][mm][n] = rm ? *(const GAS f32x4*)(xi + EPI_OFF(((t) >> 1) & 1, 2 * ((t) & 1) + mm, (t) >> 2, n) * 4 + lo4) : *(const GAS f32x4*)(xi + EPI_BLK(((t) >> 1) & 1, 2 * ((t) & 1) + mm, (t) >> 2, n) + lx); } while (0)
; #define EPI_FENCE() asm volatile("" ::: "memory")
;     __device__ __forceinline__ void operator()(const f32x4 (&acc)[2][2][4][2], const Unit& u, int wr, int wc, int fr_, int fq_, LAS unsigned char* lds) const {
;     ...
;         EPI_VEC(0); EPI_LOAD(0); EPI_FENCE(); EPI_LOAD(1); EPI_FENCE(); EPI_LOAD(2); EPI_FENCE();
;         EPI_DO(0); EPI_FENCE(); EPI_LOAD(3); EPI_FENCE();
;         EPI_DO(1); EPI_FENCE(); EPI_LOAD(4); EPI_FENCE();
;         EPI_DO(2); EPI_FENCE(); EPI_LOAD(5); EPI_FENCE();
;         EPI_DO(3); EPI_FENCE(); EPI_LOAD(6); EPI_FENCE();
;         EPI_VEC(1); EPI_FENCE();
.LBB0_1161:
	s_lshr_b32 s10, s69, 4
	s_mulk_i32 s10, 0x4800
	s_add_u32 s8, s8, s10
	s_addc_u32 s9, s9, 0
	s_lshl_b64 s[8:9], s[8:9], 2
	v_readlane_b32 s10, v255, 14
	v_lshlrev_b32_e32 v130, 5, v203
	s_add_u32 s10, s10, s8
	v_readlane_b32 s11, v255, 15
	s_addc_u32 s11, s11, s9
	v_ashrrev_i32_e32 v131, 31, v130
	v_mov_b32_e32 v168, v198
	v_lshl_add_u64 v[170:171], s[10:11], 0, v[130:131]
	v_readlane_b32 s98, v255, 24
	s_add_u32 s98, s98, s8
	v_readlane_b32 s99, v255, 21
	s_addc_u32 s99, s99, s9
	v_lshl_add_u64 v[140:141], s[98:99], 0, v[130:131]
	v_readlane_b32 s98, v254, 62
	s_add_u32 s98, s98, s4
	v_readlane_b32 s99, v255, 9
	s_addc_u32 s99, s99, s5
	v_lshl_add_u64 v[142:143], s[98:99], 0, v[130:131]
	global_load_dword v144, v[170:171], off offset:512
	global_load_dword v145, v[140:141], off
	global_load_dword v146, v[140:141], off offset:512
	global_load_dword v147, v[142:143], off
	global_load_dword v148, v[142:143], off offset:512
	v_readlane_b32 s98, v255, 30
	s_add_u32 s98, s98, s4
	v_readlane_b32 s99, v255, 33
	s_addc_u32 s99, s99, s5
	v_lshl_add_u64 v[140:141], s[98:99], 0, v[130:131]
	global_load_dword v149, v[140:141], off
	global_load_dword v139, v[140:141], off offset:512
	global_load_dwordx4 v[132:135], v[170:171], off
	s_add_u32 s28, s16, s4
	v_cndmask_b32_e64 v136, 0, 1, s[64:65]
	s_addc_u32 s29, s17, s5
	v_cmp_ne_u32_e64 s[10:11], 1, v136
	s_andn2_b64 vcc, exec, s[64:65]
	v_lshl_add_u64 v[172:173], s[28:29], 0, v[130:131]
	s_waitcnt vmcnt(0)
	v_pk_mul_f32 v[188:189], v[134:135], v[168:169] op_sel_hi:[1,0]
	v_pk_mul_f32 v[190:191], v[132:133], v[168:169] op_sel_hi:[1,0]
	s_cbranch_vccnz .LBB0_1163
	global_load_dwordx4 v[132:135], v[172:173], off
	s_waitcnt vmcnt(0)
	v_pk_mul_f32 v[188:189], v[188:189], v[134:135]
	v_pk_mul_f32 v[190:191], v[190:191], v[132:133]

; __device__ __forceinline__ unsigned xb_ld(unsigned* p)              { return __hip_atomic_load(p, __ATOMIC_RELAXED, __HIP_MEMORY_SCOPE_AGENT); }
; __device__ __forceinline__ unsigned xb_add(unsigned* p, unsigned v) { return __hip_atomic_fetch_add(p, v, __ATOMIC_RELAXED, __HIP_MEMORY_SCOPE_AGENT); }
; __device__ __forceinline__ void panel_barrier(unsigned* cnt, int tid) {
;     asm volatile("s_waitcnt vmcnt(0)" ::: "memory");
;     __syncthreads();
;     if (tid == 0) {
;         __builtin_amdgcn_s_waitcnt(0);
;         const unsigned old = xb_add(cnt, 1u), target = (old & ~3u) + 4u;
;         unsigned sp = 0u;
;         while (xb_ld(cnt) < target) { __builtin_amdgcn_s_sleep(1); if (++sp > (1u << 26)) break; }
;         __builtin_amdgcn_fence(__ATOMIC_ACQUIRE, "agent");
;         asm volatile("s_waitcnt vmcnt(0)" ::: "memory");
;     }
;     __syncthreads();
; }
.LBB0_1430:
	s_and_b64 vcc, exec, s[0:1]
	s_cbranch_vccz .LBB0_306
	v_readlane_b32 s0, v254, 1
	v_mbcnt_lo_u32_b32 v0, -1, 0
	v_mbcnt_hi_u32_b32 v0, -1, v0
	s_nop 1
	v_lshl_add_u32 v0, s0, 6, v0
	s_waitcnt vmcnt(0)
	s_waitcnt vmcnt(0) lgkmcnt(0)
	v_cmp_eq_u32_e32 vcc, 0, v0
	s_barrier
	s_and_saveexec_b64 s[0:1], vcc
	s_cbranch_execz .LBB0_305
	v_readlane_b32 s2, v254, 19
	s_lshl_b32 s2, s2, 2
	s_add_u32 s2, s92, s2
	s_addc_u32 s3, s93, 0
	v_mov_b32_e32 v0, s2
	v_add_co_u32_e32 v2, vcc, 0x12000, v0
	v_mov_b32_e32 v0, s3
	s_nop 0
	v_addc_co_u32_e32 v3, vcc, 0, v0, vcc
	s_waitcnt vmcnt(0) expcnt(0) lgkmcnt(0)
	flat_atomic_add v[2:3], v210 offset:2048
	buffer_inv sc1
	s_add_u32 s2, s2, 0x12800
	s_mov_b32 s20, 0x4000001
	s_addc_u32 s3, s3, 0
	s_mov_b64 s[4:5], 0
	s_add_i32 s101, s101, 4
	v_mov_b32_e32 v0, s101
	s_branch .LBB0_1438

; #define LAS __attribute__((address_space(3)))
; __global__ void __launch_bounds__(512, 2) mk_fwd(Args args) {
;     extern __shared__ __attribute__((aligned(16))) unsigned char lds_raw[];
;     LAS unsigned char* lds = (LAS unsigned char*)lds_raw;
;     const int tid0 = threadIdx.x, G = gridDim.x, wg = blockIdx.x;
;     const int wv = __builtin_amdgcn_readfirstlane(tid0 >> 6);
	.amdhsa_kernel _Z6mk_fwd4Args
		.amdhsa_group_segment_fixed_size 0
		.amdhsa_private_segment_fixed_size 0
		.amdhsa_kernarg_size 416
		.amdhsa_user_sgpr_count 2
		.amdhsa_user_sgpr_dispatch_ptr 0
		.amdhsa_user_sgpr_queue_ptr 0
		.amdhsa_user_sgpr_kernarg_segment_ptr 1
		.amdhsa_user_sgpr_dispatch_id 0
		.amdhsa_user_sgpr_kernarg_preload_length 0
		.amdhsa_user_sgpr_kernarg_preload_offset 0
		.amdhsa_user_sgpr_private_segment_size 0
		.amdhsa_uses_dynamic_stack 0
		.amdhsa_enable_private_segment 0
		.amdhsa_system_sgpr_workgroup_id_x 1
		.amdhsa_system_sgpr_workgroup_id_y 0
		.amdhsa_system_sgpr_workgroup_id_z 0
		.amdhsa_system_sgpr_workgroup_info 0
		.amdhsa_system_vgpr_workitem_id 0
		.amdhsa_next_free_vgpr 256
		.amdhsa_next_free_sgpr 102
		.amdhsa_accum_offset 256
		.amdhsa_reserve_vcc 1
		.amdhsa_float_round_mode_32 0
		.amdhsa_float_round_mode_16_64 0
		.amdhsa_float_denorm_mode_32 3
		.amdhsa_float_denorm_mode_16_64 3
		.amdhsa_dx10_clamp 1
		.amdhsa_ieee_mode 1
		.amdhsa_fp16_overflow 0
		.amdhsa_tg_split 0
		.amdhsa_exception_fp_ieee_invalid_op 0
		.amdhsa_exception_fp_denorm_src 0
		.amdhsa_exception_fp_ieee_div_zero 0
		.amdhsa_exception_fp_ieee_overflow 0
		.amdhsa_exception_fp_ieee_underflow 0
		.amdhsa_exception_fp_ieee_inexact 0
		.amdhsa_exception_int_div_zero 0
	.end_amdhsa_kernel

; #define LAS __attribute__((address_space(3)))
; __global__ void __launch_bounds__(512, 2) mk_fwd(Args args) {
;     extern __shared__ __attribute__((aligned(16))) unsigned char lds_raw[];
;     LAS unsigned char* lds = (LAS unsigned char*)lds_raw;
;     const int tid0 = threadIdx.x, G = gridDim.x, wg = blockIdx.x;
;     const int wv = __builtin_amdgcn_readfirstlane(tid0 >> 6);
amdhsa.kernels:
  - .agpr_count:     0
    .args:
      - .offset:         0
        .size:           160
        .value_kind:     by_value
      - .offset:         160
        .size:           4
        .value_kind:     hidden_block_count_x
      - .offset:         164
        .size:           4
        .value_kind:     hidden_block_count_y
      - .offset:         168
        .size:           4
        .value_kind:     hidden_block_count_z
      - .offset:         172
        .size:           2
        .value_kind:     hidden_group_size_x
      - .offset:         174
        .size:           2
        .value_kind:     hidden_group_size_y
      - .offset:         176
        .size:           2
        .value_kind:     hidden_group_size_z
      - .offset:         178
        .size:           2
        .value_kind:     hidden_remainder_x
      - .offset:         180
        .size:           2
        .value_kind:     hidden_remainder_y
      - .offset:         182
        .size:           2
        .value_kind:     hidden_remainder_z
      - .offset:         200
        .size:           8
        .value_kind:     hidden_global_offset_x
      - .offset:         208
        .size:           8
        .value_kind:     hidden_global_offset_y
      - .offset:         216
        .size:           8
        .value_kind:     hidden_global_offset_z
      - .offset:         224
        .size:           2
        .value_kind:     hidden_grid_dims
      - .offset:         280
        .size:           4
        .value_kind:     hidden_dynamic_lds_size
    .group_segment_fixed_size: 0
    .kernarg_segment_align: 8
    .kernarg_segment_size: 416
    .language:       OpenCL C
    .language_version:
      - 2
      - 0
    .max_flat_workgroup_size: 512
    .name:           _Z6mk_fwd4Args
    .private_segment_fixed_size: 0
    .sgpr_count:     108
    .sgpr_spill_count: 227
    .symbol:         _Z6mk_fwd4Args.kd
    .uniform_work_group_size: 1
    .uses_dynamic_stack: false
    .vgpr_count:     256
    .vgpr_spill_count: 0
    .wavefront_size: 64
